# GEMM K-loops: removed duplicate lgkmcnt(0) after s_setprio 1 and moved register-only prep from before to after the phase-closing barrier (MMA segment issue-slot trimming)
# speedup vs baseline: 1.0007x; 1.0007x over previous
.LBB0_344:
	s_ashr_i32 s37, s36, 31
	v_cmp_lt_i64_e32 vcc, s[38:39], v[142:143]
	s_lshl_b64 s[38:39], s[36:37], 20
	s_add_u32 s38, s30, s38
	s_addc_u32 s39, s31, s39
	s_and_b64 s[40:41], vcc, exec
	s_cselect_b32 s37, s39, s45
	s_cselect_b32 s72, s38, s44
	s_ashr_i32 s27, s26, 31
	s_lshl_b64 s[40:41], s[26:27], 20
	s_add_u32 s40, s56, s40
	s_addc_u32 s41, s57, s41
	s_and_b64 s[50:51], vcc, exec
	s_cselect_b32 s27, s41, s47
	s_cselect_b32 s73, s40, s46
	s_add_u32 s44, s44, 0x80080
	s_addc_u32 s45, s45, 0
	s_add_u32 s74, s46, 0x100
	v_mov_b32_e32 v2, 0
	s_addc_u32 s75, s47, 0
	s_mov_b32 s76, -2
	v_mov_b32_e32 v3, v2
	v_mov_b32_e32 v4, v2
	v_mov_b32_e32 v5, v2
	v_mov_b32_e32 v6, v2
	v_mov_b32_e32 v7, v2
	v_mov_b32_e32 v8, v2
	v_mov_b32_e32 v9, v2
	v_mov_b32_e32 v10, v2
	v_mov_b32_e32 v11, v2
	v_mov_b32_e32 v12, v2
	v_mov_b32_e32 v13, v2
	v_mov_b32_e32 v18, v2
	v_mov_b32_e32 v19, v2
	v_mov_b32_e32 v20, v2
	v_mov_b32_e32 v21, v2
	v_mov_b32_e32 v26, v2
	v_mov_b32_e32 v27, v2
	v_mov_b32_e32 v28, v2
	v_mov_b32_e32 v29, v2
	v_mov_b32_e32 v34, v2
	v_mov_b32_e32 v35, v2
	v_mov_b32_e32 v36, v2
	v_mov_b32_e32 v37, v2
	v_mov_b32_e32 v42, v2
	v_mov_b32_e32 v43, v2
	v_mov_b32_e32 v44, v2
	v_mov_b32_e32 v45, v2
	v_mov_b32_e32 v50, v2
	v_mov_b32_e32 v51, v2
	v_mov_b32_e32 v52, v2
	v_mov_b32_e32 v53, v2
	v_mov_b32_e32 v14, v2
	v_mov_b32_e32 v15, v2
	v_mov_b32_e32 v16, v2
	v_mov_b32_e32 v17, v2
	v_mov_b32_e32 v22, v2
	v_mov_b32_e32 v23, v2
	v_mov_b32_e32 v24, v2
	v_mov_b32_e32 v25, v2
	v_mov_b32_e32 v30, v2
	v_mov_b32_e32 v31, v2
	v_mov_b32_e32 v32, v2
	v_mov_b32_e32 v33, v2
	v_mov_b32_e32 v38, v2
	v_mov_b32_e32 v39, v2
	v_mov_b32_e32 v40, v2
	v_mov_b32_e32 v41, v2
	v_mov_b32_e32 v46, v2
	v_mov_b32_e32 v47, v2
	v_mov_b32_e32 v48, v2
	v_mov_b32_e32 v49, v2
	v_mov_b32_e32 v54, v2
	v_mov_b32_e32 v55, v2
	v_mov_b32_e32 v56, v2
	v_mov_b32_e32 v57, v2
	v_mov_b32_e32 v58, v2
	v_mov_b32_e32 v59, v2
	v_mov_b32_e32 v60, v2
	v_mov_b32_e32 v61, v2
	v_mov_b32_e32 v62, v2
	v_mov_b32_e32 v63, v2
	v_mov_b32_e32 v64, v2
	v_mov_b32_e32 v65, v2
	v_mov_b32_e32 v66, v2
	v_mov_b32_e32 v67, v2
	v_mov_b32_e32 v68, v2
	v_mov_b32_e32 v69, v2
	v_mov_b32_e32 v70, v2
	v_mov_b32_e32 v71, v2
	v_mov_b32_e32 v72, v2
	v_mov_b32_e32 v73, v2
	v_mov_b32_e32 v78, v2
	v_mov_b32_e32 v79, v2
	v_mov_b32_e32 v80, v2
	v_mov_b32_e32 v81, v2
	v_mov_b32_e32 v86, v2
	v_mov_b32_e32 v87, v2
	v_mov_b32_e32 v88, v2
	v_mov_b32_e32 v89, v2
	v_mov_b32_e32 v94, v2
	v_mov_b32_e32 v95, v2
	v_mov_b32_e32 v96, v2
	v_mov_b32_e32 v97, v2
	v_mov_b32_e32 v102, v2
	v_mov_b32_e32 v103, v2
	v_mov_b32_e32 v104, v2
	v_mov_b32_e32 v105, v2
	v_mov_b32_e32 v110, v2
	v_mov_b32_e32 v111, v2
	v_mov_b32_e32 v112, v2
	v_mov_b32_e32 v113, v2
	v_mov_b32_e32 v118, v2
	v_mov_b32_e32 v119, v2
	v_mov_b32_e32 v120, v2
	v_mov_b32_e32 v121, v2
	v_mov_b32_e32 v74, v2
	v_mov_b32_e32 v75, v2
	v_mov_b32_e32 v76, v2
	v_mov_b32_e32 v77, v2
	v_mov_b32_e32 v82, v2
	v_mov_b32_e32 v83, v2
	v_mov_b32_e32 v84, v2
	v_mov_b32_e32 v85, v2
	v_mov_b32_e32 v90, v2
	v_mov_b32_e32 v91, v2
	v_mov_b32_e32 v92, v2
	v_mov_b32_e32 v93, v2
	v_mov_b32_e32 v98, v2
	v_mov_b32_e32 v99, v2
	v_mov_b32_e32 v100, v2
	v_mov_b32_e32 v101, v2
	v_mov_b32_e32 v106, v2
	v_mov_b32_e32 v107, v2
	v_mov_b32_e32 v108, v2
	v_mov_b32_e32 v109, v2
	v_mov_b32_e32 v114, v2
	v_mov_b32_e32 v115, v2
	v_mov_b32_e32 v116, v2
	v_mov_b32_e32 v117, v2
	v_mov_b32_e32 v122, v2
	v_mov_b32_e32 v123, v2
	v_mov_b32_e32 v124, v2
	v_mov_b32_e32 v125, v2
	v_mov_b32_e32 v126, v2
	v_mov_b32_e32 v127, v2
	v_mov_b32_e32 v128, v2
	v_mov_b32_e32 v129, v2
	s_cmp_eq_u32 s99, 0
	s_cbranch_scc1 .LBB0_345
	ds_read_b128 v[164:167], v160
	ds_read_b128 v[168:171], v160 offset:1024
	ds_read_b128 v[172:175], v160 offset:2048
	ds_read_b128 v[176:179], v160 offset:3072
	s_add_u32 s46, s44, 0xfff80080
	s_addc_u32 s47, s45, -1
	s_cmp_eq_u32 s76, 28
	s_cselect_b32 s51, s37, s47
	s_cselect_b32 s50, s72, s46
	s_cselect_b32 s47, s27, s75
	s_cselect_b32 s46, s73, s74
	v_lshl_add_u64 v[148:149], s[44:45], 0, v[138:139]
	s_add_i32 m0, s34, 0xc000
	ds_read_b128 v[180:183], v161
	ds_read_b128 v[184:187], v161 offset:1024
	ds_read_b128 v[188:191], v161 offset:2048
	ds_read_b128 v[192:195], v161 offset:3072
	ds_read_b128 v[196:199], v161 offset:4096
	ds_read_b128 v[204:207], v161 offset:5120
	ds_read_b128 v[208:211], v161 offset:6144
	ds_read_b128 v[212:215], v161 offset:7168
	v_lshl_add_u64 v[148:149], s[44:45], 0, v[140:141]
	s_add_i32 m0, s34, 0xe000
	s_nop 0
	s_waitcnt lgkmcnt(8)
	s_barrier
	s_waitcnt lgkmcnt(0)
	s_setprio 1
	v_mfma_f32_16x16x32_bf16 v[126:129], v[164:167], v[180:183], v[126:129]
	v_mfma_f32_16x16x32_bf16 v[122:125], v[172:175], v[180:183], v[122:125]
	v_mfma_f32_16x16x32_bf16 v[114:117], v[164:167], v[188:191], v[114:117]
	v_mfma_f32_16x16x32_bf16 v[106:109], v[172:175], v[188:191], v[106:109]
	v_mfma_f32_16x16x32_bf16 v[98:101], v[164:167], v[196:199], v[98:101]
	v_mfma_f32_16x16x32_bf16 v[90:93], v[172:175], v[196:199], v[90:93]
	v_mfma_f32_16x16x32_bf16 v[82:85], v[164:167], v[208:211], v[82:85]
	v_mfma_f32_16x16x32_bf16 v[74:77], v[172:175], v[208:211], v[74:77]
	v_mfma_f32_16x16x32_bf16 v[126:129], v[168:171], v[184:187], v[126:129]
	v_mfma_f32_16x16x32_bf16 v[122:125], v[176:179], v[184:187], v[122:125]
	v_mfma_f32_16x16x32_bf16 v[114:117], v[168:171], v[192:195], v[114:117]
	v_mfma_f32_16x16x32_bf16 v[106:109], v[176:179], v[192:195], v[106:109]
	v_mfma_f32_16x16x32_bf16 v[98:101], v[168:171], v[204:207], v[98:101]
	v_mfma_f32_16x16x32_bf16 v[90:93], v[176:179], v[204:207], v[90:93]
	v_mfma_f32_16x16x32_bf16 v[82:85], v[168:171], v[212:215], v[82:85]
	v_mfma_f32_16x16x32_bf16 v[74:77], v[176:179], v[212:215], v[74:77]
	s_setprio 0
	s_barrier
	s_add_i32 s77, s65, s33
	v_lshl_add_u64 v[148:149], s[46:47], 0, v[132:133]
	s_mov_b32 m0, s77
	ds_read_b128 v[216:219], v162
	ds_read_b128 v[220:223], v162 offset:1024
	ds_read_b128 v[224:227], v162 offset:2048
	ds_read_b128 v[228:231], v162 offset:3072
	global_load_lds_dwordx4 v[148:149], off
	v_lshl_add_u64 v[232:233], s[46:47], 0, v[136:137]
	s_add_i32 m0, s77, 0x2000
	s_nop 0
	global_load_lds_dwordx4 v[232:233], off
	s_barrier
	s_waitcnt lgkmcnt(0)
	s_setprio 1
	v_mfma_f32_16x16x32_bf16 v[118:121], v[216:219], v[180:183], v[118:121]
	v_mfma_f32_16x16x32_bf16 v[110:113], v[224:227], v[180:183], v[110:113]
	v_mfma_f32_16x16x32_bf16 v[102:105], v[216:219], v[188:191], v[102:105]
	v_mfma_f32_16x16x32_bf16 v[94:97], v[224:227], v[188:191], v[94:97]
	v_mfma_f32_16x16x32_bf16 v[86:89], v[216:219], v[196:199], v[86:89]
	v_mfma_f32_16x16x32_bf16 v[78:81], v[224:227], v[196:199], v[78:81]
	v_mfma_f32_16x16x32_bf16 v[70:73], v[216:219], v[208:211], v[70:73]
	v_mfma_f32_16x16x32_bf16 v[66:69], v[224:227], v[208:211], v[66:69]
	v_mfma_f32_16x16x32_bf16 v[118:121], v[220:223], v[184:187], v[118:121]
	v_mfma_f32_16x16x32_bf16 v[110:113], v[228:231], v[184:187], v[110:113]
	v_mfma_f32_16x16x32_bf16 v[102:105], v[220:223], v[192:195], v[102:105]
	v_mfma_f32_16x16x32_bf16 v[94:97], v[228:231], v[192:195], v[94:97]
	v_mfma_f32_16x16x32_bf16 v[86:89], v[220:223], v[204:207], v[86:89]
	v_mfma_f32_16x16x32_bf16 v[78:81], v[228:231], v[204:207], v[78:81]
	v_mfma_f32_16x16x32_bf16 v[70:73], v[220:223], v[212:215], v[70:73]
	v_mfma_f32_16x16x32_bf16 v[66:69], v[228:231], v[212:215], v[66:69]
	s_setprio 0
	s_barrier
	s_mov_b32 m0, s34
	v_lshl_add_u64 v[234:235], s[50:51], 0, v[130:131]
	ds_read_b128 v[180:183], v161 offset:16384
	ds_read_b128 v[184:187], v161 offset:17408
	ds_read_b128 v[188:191], v161 offset:18432
	ds_read_b128 v[192:195], v161 offset:19456
	ds_read_b128 v[196:199], v161 offset:20480
	ds_read_b128 v[204:207], v161 offset:21504
	ds_read_b128 v[208:211], v161 offset:22528
	ds_read_b128 v[212:215], v161 offset:23552
	global_load_lds_dwordx4 v[234:235], off
	v_lshl_add_u64 v[236:237], s[50:51], 0, v[134:135]
	s_mov_b32 m0, s35
	s_nop 0
	global_load_lds_dwordx4 v[236:237], off
	s_barrier
	s_waitcnt lgkmcnt(0)
	s_setprio 1
	v_mfma_f32_16x16x32_bf16 v[62:65], v[164:167], v[180:183], v[62:65]
	v_mfma_f32_16x16x32_bf16 v[58:61], v[172:175], v[180:183], v[58:61]
	v_mfma_f32_16x16x32_bf16 v[54:57], v[164:167], v[188:191], v[54:57]
	v_mfma_f32_16x16x32_bf16 v[46:49], v[172:175], v[188:191], v[46:49]
	v_mfma_f32_16x16x32_bf16 v[38:41], v[164:167], v[196:199], v[38:41]
	v_mfma_f32_16x16x32_bf16 v[30:33], v[172:175], v[196:199], v[30:33]
	v_mfma_f32_16x16x32_bf16 v[22:25], v[164:167], v[208:211], v[22:25]
	v_mfma_f32_16x16x32_bf16 v[14:17], v[172:175], v[208:211], v[14:17]
	v_mfma_f32_16x16x32_bf16 v[62:65], v[168:171], v[184:187], v[62:65]
	v_mfma_f32_16x16x32_bf16 v[58:61], v[176:179], v[184:187], v[58:61]
	v_mfma_f32_16x16x32_bf16 v[54:57], v[168:171], v[192:195], v[54:57]
	v_mfma_f32_16x16x32_bf16 v[46:49], v[176:179], v[192:195], v[46:49]
	v_mfma_f32_16x16x32_bf16 v[38:41], v[168:171], v[204:207], v[38:41]
	v_mfma_f32_16x16x32_bf16 v[30:33], v[176:179], v[204:207], v[30:33]
	v_mfma_f32_16x16x32_bf16 v[22:25], v[168:171], v[212:215], v[22:25]
	v_mfma_f32_16x16x32_bf16 v[14:17], v[176:179], v[212:215], v[14:17]
	s_setprio 0
	s_barrier
	s_add_u32 s78, s46, 0x80000
	s_addc_u32 s79, s47, 0
	s_add_i32 s77, s66, s33
	v_lshl_add_u64 v[164:165], s[78:79], 0, v[132:133]
	s_mov_b32 m0, s77
	s_nop 0
	global_load_lds_dwordx4 v[164:165], off
	v_lshl_add_u64 v[164:165], s[78:79], 0, v[136:137]
	s_add_i32 m0, s77, 0x2000
	s_nop 0
	global_load_lds_dwordx4 v[164:165], off
	s_waitcnt vmcnt(22)
	s_barrier
	s_setprio 1
	v_mfma_f32_16x16x32_bf16 v[50:53], v[216:219], v[180:183], v[50:53]
	v_mfma_f32_16x16x32_bf16 v[42:45], v[224:227], v[180:183], v[42:45]
	v_mfma_f32_16x16x32_bf16 v[34:37], v[216:219], v[188:191], v[34:37]
	v_mfma_f32_16x16x32_bf16 v[26:29], v[224:227], v[188:191], v[26:29]
	v_mfma_f32_16x16x32_bf16 v[18:21], v[216:219], v[196:199], v[18:21]
	v_mfma_f32_16x16x32_bf16 v[10:13], v[224:227], v[196:199], v[10:13]
	v_mfma_f32_16x16x32_bf16 v[6:9], v[216:219], v[208:211], v[6:9]
	v_mfma_f32_16x16x32_bf16 v[2:5], v[224:227], v[208:211], v[2:5]
	v_mfma_f32_16x16x32_bf16 v[50:53], v[220:223], v[184:187], v[50:53]
	v_mfma_f32_16x16x32_bf16 v[42:45], v[228:231], v[184:187], v[42:45]
	v_mfma_f32_16x16x32_bf16 v[34:37], v[220:223], v[192:195], v[34:37]
	v_mfma_f32_16x16x32_bf16 v[26:29], v[228:231], v[192:195], v[26:29]
	v_mfma_f32_16x16x32_bf16 v[18:21], v[220:223], v[204:207], v[18:21]
	v_mfma_f32_16x16x32_bf16 v[10:13], v[228:231], v[204:207], v[10:13]
	v_mfma_f32_16x16x32_bf16 v[6:9], v[220:223], v[212:215], v[6:9]
	v_mfma_f32_16x16x32_bf16 v[2:5], v[228:231], v[212:215], v[2:5]
	s_setprio 0
	s_barrier
	s_branch .Ltb_mid_g1
.LBB0_345:
	ds_read_b128 v[164:167], v160
	ds_read_b128 v[168:171], v160 offset:1024
	ds_read_b128 v[172:175], v160 offset:2048
	ds_read_b128 v[176:179], v160 offset:3072
	s_add_u32 s46, s44, 0xfff80080
	s_addc_u32 s47, s45, -1
	s_cmp_eq_u32 s76, 28
	s_cselect_b32 s51, s37, s47
	s_cselect_b32 s50, s72, s46
	s_cselect_b32 s47, s27, s75
	s_cselect_b32 s46, s73, s74
	v_lshl_add_u64 v[148:149], s[44:45], 0, v[138:139]
	s_add_i32 m0, s34, 0xc000
	ds_read_b128 v[180:183], v161
	ds_read_b128 v[184:187], v161 offset:1024
	ds_read_b128 v[188:191], v161 offset:2048
	ds_read_b128 v[192:195], v161 offset:3072
	ds_read_b128 v[196:199], v161 offset:4096
	ds_read_b128 v[204:207], v161 offset:5120
	ds_read_b128 v[208:211], v161 offset:6144
	ds_read_b128 v[212:215], v161 offset:7168
	global_load_lds_dwordx4 v[148:149], off
	v_lshl_add_u64 v[148:149], s[44:45], 0, v[140:141]
	s_add_i32 m0, s34, 0xe000
	s_nop 0
	global_load_lds_dwordx4 v[148:149], off
	s_waitcnt lgkmcnt(8)
	s_barrier
	s_waitcnt lgkmcnt(0)
	s_setprio 1
	v_mfma_f32_16x16x32_bf16 v[126:129], v[164:167], v[180:183], v[126:129]
	v_mfma_f32_16x16x32_bf16 v[122:125], v[172:175], v[180:183], v[122:125]
	v_mfma_f32_16x16x32_bf16 v[114:117], v[164:167], v[188:191], v[114:117]
	v_mfma_f32_16x16x32_bf16 v[106:109], v[172:175], v[188:191], v[106:109]
	v_mfma_f32_16x16x32_bf16 v[98:101], v[164:167], v[196:199], v[98:101]
	v_mfma_f32_16x16x32_bf16 v[90:93], v[172:175], v[196:199], v[90:93]
	v_mfma_f32_16x16x32_bf16 v[82:85], v[164:167], v[208:211], v[82:85]
	v_mfma_f32_16x16x32_bf16 v[74:77], v[172:175], v[208:211], v[74:77]
	v_mfma_f32_16x16x32_bf16 v[126:129], v[168:171], v[184:187], v[126:129]
	v_mfma_f32_16x16x32_bf16 v[122:125], v[176:179], v[184:187], v[122:125]
	v_mfma_f32_16x16x32_bf16 v[114:117], v[168:171], v[192:195], v[114:117]
	v_mfma_f32_16x16x32_bf16 v[106:109], v[176:179], v[192:195], v[106:109]
	v_mfma_f32_16x16x32_bf16 v[98:101], v[168:171], v[204:207], v[98:101]
	v_mfma_f32_16x16x32_bf16 v[90:93], v[176:179], v[204:207], v[90:93]
	v_mfma_f32_16x16x32_bf16 v[82:85], v[168:171], v[212:215], v[82:85]
	v_mfma_f32_16x16x32_bf16 v[74:77], v[176:179], v[212:215], v[74:77]
	s_setprio 0
	s_barrier
	s_add_i32 s77, s65, s33
	v_lshl_add_u64 v[148:149], s[46:47], 0, v[132:133]
	s_mov_b32 m0, s77
	ds_read_b128 v[216:219], v162
	ds_read_b128 v[220:223], v162 offset:1024
	ds_read_b128 v[224:227], v162 offset:2048
	ds_read_b128 v[228:231], v162 offset:3072
	global_load_lds_dwordx4 v[148:149], off
	v_lshl_add_u64 v[232:233], s[46:47], 0, v[136:137]
	s_add_i32 m0, s77, 0x2000
	s_nop 0
	global_load_lds_dwordx4 v[232:233], off
	s_barrier
	s_waitcnt lgkmcnt(0)
	s_setprio 1
	v_mfma_f32_16x16x32_bf16 v[118:121], v[216:219], v[180:183], v[118:121]
	v_mfma_f32_16x16x32_bf16 v[110:113], v[224:227], v[180:183], v[110:113]
	v_mfma_f32_16x16x32_bf16 v[102:105], v[216:219], v[188:191], v[102:105]
	v_mfma_f32_16x16x32_bf16 v[94:97], v[224:227], v[188:191], v[94:97]
	v_mfma_f32_16x16x32_bf16 v[86:89], v[216:219], v[196:199], v[86:89]
	v_mfma_f32_16x16x32_bf16 v[78:81], v[224:227], v[196:199], v[78:81]
	v_mfma_f32_16x16x32_bf16 v[70:73], v[216:219], v[208:211], v[70:73]
	v_mfma_f32_16x16x32_bf16 v[66:69], v[224:227], v[208:211], v[66:69]
	v_mfma_f32_16x16x32_bf16 v[118:121], v[220:223], v[184:187], v[118:121]
	v_mfma_f32_16x16x32_bf16 v[110:113], v[228:231], v[184:187], v[110:113]
	v_mfma_f32_16x16x32_bf16 v[102:105], v[220:223], v[192:195], v[102:105]
	v_mfma_f32_16x16x32_bf16 v[94:97], v[228:231], v[192:195], v[94:97]
	v_mfma_f32_16x16x32_bf16 v[86:89], v[220:223], v[204:207], v[86:89]
	v_mfma_f32_16x16x32_bf16 v[78:81], v[228:231], v[204:207], v[78:81]
	v_mfma_f32_16x16x32_bf16 v[70:73], v[220:223], v[212:215], v[70:73]
	v_mfma_f32_16x16x32_bf16 v[66:69], v[228:231], v[212:215], v[66:69]
	s_setprio 0
	s_barrier
	s_mov_b32 m0, s34
	v_lshl_add_u64 v[234:235], s[50:51], 0, v[130:131]
	ds_read_b128 v[180:183], v161 offset:16384
	ds_read_b128 v[184:187], v161 offset:17408
	ds_read_b128 v[188:191], v161 offset:18432
	ds_read_b128 v[192:195], v161 offset:19456
	ds_read_b128 v[196:199], v161 offset:20480
	ds_read_b128 v[204:207], v161 offset:21504
	ds_read_b128 v[208:211], v161 offset:22528
	ds_read_b128 v[212:215], v161 offset:23552
	global_load_lds_dwordx4 v[234:235], off
	v_lshl_add_u64 v[236:237], s[50:51], 0, v[134:135]
	s_mov_b32 m0, s35
	s_nop 0
	global_load_lds_dwordx4 v[236:237], off
	s_barrier
	s_waitcnt lgkmcnt(0)
	s_setprio 1
	v_mfma_f32_16x16x32_bf16 v[62:65], v[164:167], v[180:183], v[62:65]
	v_mfma_f32_16x16x32_bf16 v[58:61], v[172:175], v[180:183], v[58:61]
	v_mfma_f32_16x16x32_bf16 v[54:57], v[164:167], v[188:191], v[54:57]
	v_mfma_f32_16x16x32_bf16 v[46:49], v[172:175], v[188:191], v[46:49]
	v_mfma_f32_16x16x32_bf16 v[38:41], v[164:167], v[196:199], v[38:41]
	v_mfma_f32_16x16x32_bf16 v[30:33], v[172:175], v[196:199], v[30:33]
	v_mfma_f32_16x16x32_bf16 v[22:25], v[164:167], v[208:211], v[22:25]
	v_mfma_f32_16x16x32_bf16 v[14:17], v[172:175], v[208:211], v[14:17]
	v_mfma_f32_16x16x32_bf16 v[62:65], v[168:171], v[184:187], v[62:65]
	v_mfma_f32_16x16x32_bf16 v[58:61], v[176:179], v[184:187], v[58:61]
	v_mfma_f32_16x16x32_bf16 v[54:57], v[168:171], v[192:195], v[54:57]
	v_mfma_f32_16x16x32_bf16 v[46:49], v[176:179], v[192:195], v[46:49]
	v_mfma_f32_16x16x32_bf16 v[38:41], v[168:171], v[204:207], v[38:41]
	v_mfma_f32_16x16x32_bf16 v[30:33], v[176:179], v[204:207], v[30:33]
	v_mfma_f32_16x16x32_bf16 v[22:25], v[168:171], v[212:215], v[22:25]
	v_mfma_f32_16x16x32_bf16 v[14:17], v[176:179], v[212:215], v[14:17]
	s_setprio 0
	s_barrier
	s_add_u32 s78, s46, 0x80000
	s_addc_u32 s79, s47, 0
	s_add_i32 s77, s66, s33
	v_lshl_add_u64 v[164:165], s[78:79], 0, v[132:133]
	s_mov_b32 m0, s77
	s_nop 0
	global_load_lds_dwordx4 v[164:165], off
	v_lshl_add_u64 v[164:165], s[78:79], 0, v[136:137]
	s_add_i32 m0, s77, 0x2000
	s_nop 0
	global_load_lds_dwordx4 v[164:165], off
	s_waitcnt vmcnt(6)
	s_barrier
	s_setprio 1
	v_mfma_f32_16x16x32_bf16 v[50:53], v[216:219], v[180:183], v[50:53]
	v_mfma_f32_16x16x32_bf16 v[42:45], v[224:227], v[180:183], v[42:45]
	v_mfma_f32_16x16x32_bf16 v[34:37], v[216:219], v[188:191], v[34:37]
	v_mfma_f32_16x16x32_bf16 v[26:29], v[224:227], v[188:191], v[26:29]
	v_mfma_f32_16x16x32_bf16 v[18:21], v[216:219], v[196:199], v[18:21]
	v_mfma_f32_16x16x32_bf16 v[10:13], v[224:227], v[196:199], v[10:13]
	v_mfma_f32_16x16x32_bf16 v[6:9], v[216:219], v[208:211], v[6:9]
	v_mfma_f32_16x16x32_bf16 v[2:5], v[224:227], v[208:211], v[2:5]
	v_mfma_f32_16x16x32_bf16 v[50:53], v[220:223], v[184:187], v[50:53]
	v_mfma_f32_16x16x32_bf16 v[42:45], v[228:231], v[184:187], v[42:45]
	v_mfma_f32_16x16x32_bf16 v[34:37], v[220:223], v[192:195], v[34:37]
	v_mfma_f32_16x16x32_bf16 v[26:29], v[228:231], v[192:195], v[26:29]
	v_mfma_f32_16x16x32_bf16 v[18:21], v[220:223], v[204:207], v[18:21]
	v_mfma_f32_16x16x32_bf16 v[10:13], v[228:231], v[204:207], v[10:13]
	v_mfma_f32_16x16x32_bf16 v[6:9], v[220:223], v[212:215], v[6:9]
	v_mfma_f32_16x16x32_bf16 v[2:5], v[228:231], v[212:215], v[2:5]
	s_setprio 0
	s_barrier
.Ltb_mid_g1:
	s_add_i32 s77, 0, 0x18000
	v_add_u32_e32 v163, s77, v158
	ds_read_b128 v[164:167], v163
	ds_read_b128 v[168:171], v163 offset:1024
	ds_read_b128 v[172:175], v163 offset:2048
	ds_read_b128 v[176:179], v163 offset:3072
	s_add_u32 s50, s50, 0x80000
	s_addc_u32 s51, s51, 0
	s_mov_b32 m0, s43
	v_lshl_add_u64 v[216:217], s[50:51], 0, v[130:131]
	ds_read_b128 v[180:183], v161 offset:32768
	ds_read_b128 v[184:187], v161 offset:33792
	ds_read_b128 v[188:191], v161 offset:34816
	ds_read_b128 v[192:195], v161 offset:35840
	ds_read_b128 v[196:199], v161 offset:36864
	ds_read_b128 v[204:207], v161 offset:37888
	ds_read_b128 v[208:211], v161 offset:38912
	ds_read_b128 v[212:215], v161 offset:39936
	global_load_lds_dwordx4 v[216:217], off
	v_lshl_add_u64 v[216:217], s[50:51], 0, v[134:135]
	s_mov_b32 m0, s60
	s_nop 0
	global_load_lds_dwordx4 v[216:217], off
	s_waitcnt lgkmcnt(8)
	s_barrier
	s_waitcnt lgkmcnt(0)
	s_setprio 1
	v_mfma_f32_16x16x32_bf16 v[126:129], v[164:167], v[180:183], v[126:129]
	v_mfma_f32_16x16x32_bf16 v[122:125], v[172:175], v[180:183], v[122:125]
	v_mfma_f32_16x16x32_bf16 v[114:117], v[164:167], v[188:191], v[114:117]
	v_mfma_f32_16x16x32_bf16 v[106:109], v[172:175], v[188:191], v[106:109]
	v_mfma_f32_16x16x32_bf16 v[98:101], v[164:167], v[196:199], v[98:101]
	v_mfma_f32_16x16x32_bf16 v[90:93], v[172:175], v[196:199], v[90:93]
	v_mfma_f32_16x16x32_bf16 v[82:85], v[164:167], v[208:211], v[82:85]
	v_mfma_f32_16x16x32_bf16 v[74:77], v[172:175], v[208:211], v[74:77]
	v_mfma_f32_16x16x32_bf16 v[126:129], v[168:171], v[184:187], v[126:129]
	v_mfma_f32_16x16x32_bf16 v[122:125], v[176:179], v[184:187], v[122:125]
	v_mfma_f32_16x16x32_bf16 v[114:117], v[168:171], v[192:195], v[114:117]
	v_mfma_f32_16x16x32_bf16 v[106:109], v[176:179], v[192:195], v[106:109]
	v_mfma_f32_16x16x32_bf16 v[98:101], v[168:171], v[204:207], v[98:101]
	v_mfma_f32_16x16x32_bf16 v[90:93], v[176:179], v[204:207], v[90:93]
	v_mfma_f32_16x16x32_bf16 v[82:85], v[168:171], v[212:215], v[82:85]
	v_mfma_f32_16x16x32_bf16 v[74:77], v[176:179], v[212:215], v[74:77]
	s_setprio 0
	s_barrier
	s_add_i32 s50, 0, 0x1c000
	s_add_i32 s51, s77, s33
	v_add_u32_e32 v163, s50, v158
	v_lshl_add_u64 v[148:149], v[148:149], 0, s[8:9]
	s_mov_b32 m0, s51
	ds_read_b128 v[216:219], v163
	ds_read_b128 v[220:223], v163 offset:1024
	ds_read_b128 v[224:227], v163 offset:2048
	ds_read_b128 v[228:231], v163 offset:3072
	global_load_lds_dwordx4 v[148:149], off
	v_lshl_add_u64 v[148:149], v[232:233], 0, s[8:9]
	s_add_i32 m0, s51, 0x2000
	s_nop 0
	global_load_lds_dwordx4 v[148:149], off
	s_barrier
	s_waitcnt lgkmcnt(0)
	s_setprio 1
	v_mfma_f32_16x16x32_bf16 v[118:121], v[216:219], v[180:183], v[118:121]
	v_mfma_f32_16x16x32_bf16 v[110:113], v[224:227], v[180:183], v[110:113]
	v_mfma_f32_16x16x32_bf16 v[102:105], v[216:219], v[188:191], v[102:105]
	v_mfma_f32_16x16x32_bf16 v[94:97], v[224:227], v[188:191], v[94:97]
	v_mfma_f32_16x16x32_bf16 v[86:89], v[216:219], v[196:199], v[86:89]
	v_mfma_f32_16x16x32_bf16 v[78:81], v[224:227], v[196:199], v[78:81]
	v_mfma_f32_16x16x32_bf16 v[70:73], v[216:219], v[208:211], v[70:73]
	v_mfma_f32_16x16x32_bf16 v[66:69], v[224:227], v[208:211], v[66:69]
	v_mfma_f32_16x16x32_bf16 v[118:121], v[220:223], v[184:187], v[118:121]
	v_mfma_f32_16x16x32_bf16 v[110:113], v[228:231], v[184:187], v[110:113]
	v_mfma_f32_16x16x32_bf16 v[102:105], v[220:223], v[192:195], v[102:105]
	v_mfma_f32_16x16x32_bf16 v[94:97], v[228:231], v[192:195], v[94:97]
	v_mfma_f32_16x16x32_bf16 v[86:89], v[220:223], v[204:207], v[86:89]
	v_mfma_f32_16x16x32_bf16 v[78:81], v[228:231], v[204:207], v[78:81]
	v_mfma_f32_16x16x32_bf16 v[70:73], v[220:223], v[212:215], v[70:73]
	v_mfma_f32_16x16x32_bf16 v[66:69], v[228:231], v[212:215], v[66:69]
	s_setprio 0
	s_barrier
	s_mov_b32 m0, s62
	v_lshl_add_u64 v[148:149], v[234:235], 0, s[8:9]
	ds_read_b128 v[180:183], v161 offset:49152
	ds_read_b128 v[184:187], v161 offset:50176
	ds_read_b128 v[188:191], v161 offset:51200
	ds_read_b128 v[192:195], v161 offset:52224
	ds_read_b128 v[196:199], v161 offset:53248
	ds_read_b128 v[204:207], v161 offset:54272
	ds_read_b128 v[208:211], v161 offset:55296
	ds_read_b128 v[212:215], v161 offset:56320
	global_load_lds_dwordx4 v[148:149], off
	v_lshl_add_u64 v[148:149], v[236:237], 0, s[8:9]
	s_mov_b32 m0, s63
	s_nop 0
	global_load_lds_dwordx4 v[148:149], off
	s_barrier
	s_waitcnt lgkmcnt(0)
	s_setprio 1
	v_mfma_f32_16x16x32_bf16 v[62:65], v[164:167], v[180:183], v[62:65]
	v_mfma_f32_16x16x32_bf16 v[58:61], v[172:175], v[180:183], v[58:61]
	v_mfma_f32_16x16x32_bf16 v[54:57], v[164:167], v[188:191], v[54:57]
	v_mfma_f32_16x16x32_bf16 v[46:49], v[172:175], v[188:191], v[46:49]
	v_mfma_f32_16x16x32_bf16 v[38:41], v[164:167], v[196:199], v[38:41]
	v_mfma_f32_16x16x32_bf16 v[30:33], v[172:175], v[196:199], v[30:33]
	v_mfma_f32_16x16x32_bf16 v[22:25], v[164:167], v[208:211], v[22:25]
	v_mfma_f32_16x16x32_bf16 v[14:17], v[172:175], v[208:211], v[14:17]
	v_mfma_f32_16x16x32_bf16 v[62:65], v[168:171], v[184:187], v[62:65]
	v_mfma_f32_16x16x32_bf16 v[58:61], v[176:179], v[184:187], v[58:61]
	v_mfma_f32_16x16x32_bf16 v[54:57], v[168:171], v[192:195], v[54:57]
	v_mfma_f32_16x16x32_bf16 v[46:49], v[176:179], v[192:195], v[46:49]
	v_mfma_f32_16x16x32_bf16 v[38:41], v[168:171], v[204:207], v[38:41]
	v_mfma_f32_16x16x32_bf16 v[30:33], v[176:179], v[204:207], v[30:33]
	v_mfma_f32_16x16x32_bf16 v[22:25], v[168:171], v[212:215], v[22:25]
	v_mfma_f32_16x16x32_bf16 v[14:17], v[176:179], v[212:215], v[14:17]
	s_setprio 0
	s_barrier
	s_add_u32 s46, s46, 0x80080
	s_addc_u32 s47, s47, 0
	s_add_i32 s50, s50, s33
	v_lshl_add_u64 v[148:149], s[46:47], 0, v[132:133]
	s_mov_b32 m0, s50
	s_nop 0
	global_load_lds_dwordx4 v[148:149], off
	v_lshl_add_u64 v[148:149], s[46:47], 0, v[136:137]
	s_add_i32 m0, s50, 0x2000
	s_nop 0
	global_load_lds_dwordx4 v[148:149], off
	s_waitcnt vmcnt(6)
	s_barrier
	s_setprio 1
	v_mfma_f32_16x16x32_bf16 v[50:53], v[216:219], v[180:183], v[50:53]
	v_mfma_f32_16x16x32_bf16 v[42:45], v[224:227], v[180:183], v[42:45]
	v_mfma_f32_16x16x32_bf16 v[34:37], v[216:219], v[188:191], v[34:37]
	v_mfma_f32_16x16x32_bf16 v[26:29], v[224:227], v[188:191], v[26:29]
	v_mfma_f32_16x16x32_bf16 v[18:21], v[216:219], v[196:199], v[18:21]
	v_mfma_f32_16x16x32_bf16 v[10:13], v[224:227], v[196:199], v[10:13]
	v_mfma_f32_16x16x32_bf16 v[6:9], v[216:219], v[208:211], v[6:9]
	v_mfma_f32_16x16x32_bf16 v[2:5], v[224:227], v[208:211], v[2:5]
	v_mfma_f32_16x16x32_bf16 v[50:53], v[220:223], v[184:187], v[50:53]
	v_mfma_f32_16x16x32_bf16 v[42:45], v[228:231], v[184:187], v[42:45]
	v_mfma_f32_16x16x32_bf16 v[34:37], v[220:223], v[192:195], v[34:37]
	v_mfma_f32_16x16x32_bf16 v[26:29], v[228:231], v[192:195], v[26:29]
	v_mfma_f32_16x16x32_bf16 v[18:21], v[220:223], v[204:207], v[18:21]
	v_mfma_f32_16x16x32_bf16 v[10:13], v[228:231], v[204:207], v[10:13]
	v_mfma_f32_16x16x32_bf16 v[6:9], v[220:223], v[212:215], v[6:9]
	v_mfma_f32_16x16x32_bf16 v[2:5], v[228:231], v[212:215], v[2:5]
	s_setprio 0
	s_barrier
	s_add_i32 s76, s76, 2
	s_add_u32 s44, s44, 0x100
	s_addc_u32 s45, s45, 0
	s_add_u32 s74, s74, 0x100
	s_addc_u32 s75, s75, 0
	s_cmp_gt_u32 s76, 29
	s_cbranch_scc0 .LBB0_345
	s_add_u32 s100, s72, 0x80080
	s_addc_u32 s101, s37, 0
	v_lshl_add_u64 v[148:149], s[100:101], 0, v[138:139]
	s_add_i32 m0, s34, 0xc000
	s_nop 0
	global_load_lds_dwordx4 v[148:149], off
	v_lshl_add_u64 v[148:149], s[100:101], 0, v[140:141]
	s_add_i32 m0, s34, 0xe000
	s_nop 0
	global_load_lds_dwordx4 v[148:149], off
	s_mov_b32 s99, 1
	v_lshl_add_u32 v164, s42, 8, v157
	v_lshl_or_b32 v148, s71, 8, v159
	v_ashrrev_i32_e32 v165, 31, v164
	v_ashrrev_i32_e32 v149, 31, v148
	v_lshlrev_b64 v[166:167], 16, v[164:165]
	v_lshl_add_u64 v[166:167], s[6:7], 0, v[166:167]
	v_lshlrev_b64 v[168:169], 1, v[148:149]
	v_lshl_add_u64 v[148:149], v[166:167], 0, v[168:169]
	v_cvt_pk_bf16_f32 v126, v126, v127
	v_cvt_pk_bf16_f32 v127, v128, v129
	v_cvt_pk_bf16_f32 v128, v122, v123
	v_cvt_pk_bf16_f32 v129, v124, v125
	global_store_dwordx4 v[148:149], v[126:129], off
	v_cvt_pk_bf16_f32 v118, v118, v119
	v_cvt_pk_bf16_f32 v119, v120, v121
	v_cvt_pk_bf16_f32 v120, v110, v111
	v_or_b32_e32 v110, 16, v164
	v_ashrrev_i32_e32 v111, 31, v110
	v_lshlrev_b64 v[110:111], 16, v[110:111]
	v_lshl_add_u64 v[110:111], s[6:7], 0, v[110:111]
	v_cvt_pk_bf16_f32 v121, v112, v113
	global_store_dwordx4 v[148:149], v[118:121], off offset:256
	s_mov_b32 s71, s26
	s_mov_b32 s42, s36
	v_lshl_add_u64 v[118:119], v[110:111], 0, v[168:169]
	v_cvt_pk_bf16_f32 v110, v114, v115
	v_cvt_pk_bf16_f32 v111, v116, v117
	v_cvt_pk_bf16_f32 v112, v106, v107
	v_cvt_pk_bf16_f32 v113, v108, v109
	global_store_dwordx4 v[118:119], v[110:113], off
	v_cvt_pk_bf16_f32 v102, v102, v103
	v_cvt_pk_bf16_f32 v103, v104, v105
	v_cvt_pk_bf16_f32 v104, v94, v95
	v_or_b32_e32 v94, 32, v164
	v_ashrrev_i32_e32 v95, 31, v94
	v_lshlrev_b64 v[94:95], 16, v[94:95]
	v_lshl_add_u64 v[94:95], s[6:7], 0, v[94:95]
	v_cvt_pk_bf16_f32 v105, v96, v97
	global_store_dwordx4 v[118:119], v[102:105], off offset:256
	s_mov_b64 s[46:47], s[40:41]
	s_mov_b64 s[44:45], s[38:39]
	v_lshl_add_u64 v[102:103], v[94:95], 0, v[168:169]
	v_cvt_pk_bf16_f32 v94, v98, v99
	v_cvt_pk_bf16_f32 v95, v100, v101
	v_cvt_pk_bf16_f32 v96, v90, v91
	v_cvt_pk_bf16_f32 v97, v92, v93
	global_store_dwordx4 v[102:103], v[94:97], off
	v_cvt_pk_bf16_f32 v86, v86, v87
	v_cvt_pk_bf16_f32 v87, v88, v89
	v_cvt_pk_bf16_f32 v88, v78, v79
	v_or_b32_e32 v78, 48, v164
	v_ashrrev_i32_e32 v79, 31, v78
	v_lshlrev_b64 v[78:79], 16, v[78:79]
	v_lshl_add_u64 v[78:79], s[6:7], 0, v[78:79]
	v_cvt_pk_bf16_f32 v89, v80, v81
	global_store_dwordx4 v[102:103], v[86:89], off offset:256
	s_nop 1
	v_lshl_add_u64 v[86:87], v[78:79], 0, v[168:169]
	v_cvt_pk_bf16_f32 v78, v82, v83
	v_cvt_pk_bf16_f32 v79, v84, v85
	v_cvt_pk_bf16_f32 v80, v74, v75
	v_cvt_pk_bf16_f32 v81, v76, v77
	global_store_dwordx4 v[86:87], v[78:81], off
	v_cvt_pk_bf16_f32 v70, v70, v71
	v_cvt_pk_bf16_f32 v71, v72, v73
	v_cvt_pk_bf16_f32 v72, v66, v67
	v_cvt_pk_bf16_f32 v73, v68, v69
	global_store_dwordx4 v[86:87], v[70:73], off offset:256
	v_cvt_pk_bf16_f32 v62, v62, v63
	v_cvt_pk_bf16_f32 v63, v64, v65
	v_cvt_pk_bf16_f32 v64, v58, v59
	v_add_co_u32_e32 v58, vcc, s67, v148
	v_lshl_add_u64 v[66:67], v[148:149], 0, s[10:11]
	s_nop 0
	v_addc_co_u32_e32 v59, vcc, 0, v149, vcc
	v_cvt_pk_bf16_f32 v65, v60, v61
	global_store_dwordx4 v[58:59], v[62:65], off
	v_cvt_pk_bf16_f32 v50, v50, v51
	v_cvt_pk_bf16_f32 v51, v52, v53
	v_cvt_pk_bf16_f32 v52, v42, v43
	v_cvt_pk_bf16_f32 v53, v44, v45
	global_store_dwordx4 v[66:67], v[50:53], off offset:256
	v_cvt_pk_bf16_f32 v42, v54, v55
	v_cvt_pk_bf16_f32 v43, v56, v57
	v_cvt_pk_bf16_f32 v44, v46, v47
	v_add_co_u32_e32 v46, vcc, s68, v148
	s_nop 0
	v_lshl_add_u64 v[50:51], v[148:149], 0, s[16:17]
	v_addc_co_u32_e32 v47, vcc, 0, v149, vcc
	v_cvt_pk_bf16_f32 v45, v48, v49
	global_store_dwordx4 v[46:47], v[42:45], off
	v_cvt_pk_bf16_f32 v34, v34, v35
	v_cvt_pk_bf16_f32 v35, v36, v37
	v_cvt_pk_bf16_f32 v36, v26, v27
	v_cvt_pk_bf16_f32 v37, v28, v29
	global_store_dwordx4 v[50:51], v[34:37], off offset:256
	v_cvt_pk_bf16_f32 v26, v38, v39
	v_cvt_pk_bf16_f32 v27, v40, v41
	v_cvt_pk_bf16_f32 v28, v30, v31
	v_add_co_u32_e32 v30, vcc, s69, v148
	s_nop 0
	v_lshl_add_u64 v[34:35], v[148:149], 0, s[18:19]
	v_addc_co_u32_e32 v31, vcc, 0, v149, vcc
	v_cvt_pk_bf16_f32 v29, v32, v33
	global_store_dwordx4 v[30:31], v[26:29], off
	v_cvt_pk_bf16_f32 v18, v18, v19
	v_cvt_pk_bf16_f32 v19, v20, v21
	v_cvt_pk_bf16_f32 v20, v10, v11
	v_cvt_pk_bf16_f32 v21, v12, v13
	global_store_dwordx4 v[34:35], v[18:21], off offset:256
	v_cvt_pk_bf16_f32 v10, v22, v23
	v_cvt_pk_bf16_f32 v11, v24, v25
	v_cvt_pk_bf16_f32 v12, v14, v15
	v_add_co_u32_e32 v14, vcc, s70, v148
	s_nop 0
	v_lshl_add_u64 v[18:19], v[148:149], 0, s[24:25]
	v_addc_co_u32_e32 v15, vcc, 0, v149, vcc
	s_and_b64 vcc, exec, s[0:1]
	v_cvt_pk_bf16_f32 v13, v16, v17
	global_store_dwordx4 v[14:15], v[10:13], off
	v_cvt_pk_bf16_f32 v6, v6, v7
	v_cvt_pk_bf16_f32 v7, v8, v9
	v_cvt_pk_bf16_f32 v8, v2, v3
	v_cvt_pk_bf16_f32 v9, v4, v5
	global_store_dwordx4 v[18:19], v[6:9], off offset:256
	s_cbranch_vccz .LBB0_338
	s_waitcnt vmcnt(0)
	s_cmpk_gt_u32 s3, 0xff
	s_cbranch_scc1 .LBB0_349
	s_barrier

.LBB0_365:
	ds_read_b128 v[158:161], v150
	ds_read_b128 v[162:165], v150 offset:1024
	ds_read_b128 v[166:169], v150 offset:2048
	ds_read_b128 v[170:173], v150 offset:3072
	s_add_u32 s46, s44, 0xfff80080
	s_addc_u32 s47, s45, -1
	s_cmp_eq_u32 s76, 28
	s_cselect_b32 s51, s37, s47
	s_cselect_b32 s50, s72, s46
	s_cselect_b32 s47, s27, s75
	s_cselect_b32 s46, s73, s74
	v_lshl_add_u64 v[148:149], s[44:45], 0, v[138:139]
	s_add_i32 m0, s34, 0xc000
	ds_read_b128 v[174:177], v151
	ds_read_b128 v[178:181], v151 offset:1024
	ds_read_b128 v[182:185], v151 offset:2048
	ds_read_b128 v[186:189], v151 offset:3072
	ds_read_b128 v[190:193], v151 offset:4096
	ds_read_b128 v[194:197], v151 offset:5120
	ds_read_b128 v[204:207], v151 offset:6144
	ds_read_b128 v[208:211], v151 offset:7168
	global_load_lds_dwordx4 v[148:149], off
	v_lshl_add_u64 v[148:149], s[44:45], 0, v[140:141]
	s_add_i32 m0, s34, 0xe000
	s_nop 0
	global_load_lds_dwordx4 v[148:149], off
	s_waitcnt lgkmcnt(8)
	s_barrier
	s_waitcnt lgkmcnt(0)
	s_setprio 1
	v_mfma_f32_16x16x32_bf16 v[126:129], v[158:161], v[174:177], v[126:129]
	v_mfma_f32_16x16x32_bf16 v[122:125], v[166:169], v[174:177], v[122:125]
	v_mfma_f32_16x16x32_bf16 v[114:117], v[158:161], v[182:185], v[114:117]
	v_mfma_f32_16x16x32_bf16 v[106:109], v[166:169], v[182:185], v[106:109]
	v_mfma_f32_16x16x32_bf16 v[98:101], v[158:161], v[190:193], v[98:101]
	v_mfma_f32_16x16x32_bf16 v[90:93], v[166:169], v[190:193], v[90:93]
	v_mfma_f32_16x16x32_bf16 v[82:85], v[158:161], v[204:207], v[82:85]
	v_mfma_f32_16x16x32_bf16 v[74:77], v[166:169], v[204:207], v[74:77]
	v_mfma_f32_16x16x32_bf16 v[126:129], v[162:165], v[178:181], v[126:129]
	v_mfma_f32_16x16x32_bf16 v[122:125], v[170:173], v[178:181], v[122:125]
	v_mfma_f32_16x16x32_bf16 v[114:117], v[162:165], v[186:189], v[114:117]
	v_mfma_f32_16x16x32_bf16 v[106:109], v[170:173], v[186:189], v[106:109]
	v_mfma_f32_16x16x32_bf16 v[98:101], v[162:165], v[194:197], v[98:101]
	v_mfma_f32_16x16x32_bf16 v[90:93], v[170:173], v[194:197], v[90:93]
	v_mfma_f32_16x16x32_bf16 v[82:85], v[162:165], v[208:211], v[82:85]
	v_mfma_f32_16x16x32_bf16 v[74:77], v[170:173], v[208:211], v[74:77]
	s_setprio 0
	s_barrier
	s_add_i32 s77, s65, s33
	v_lshl_add_u64 v[148:149], s[46:47], 0, v[132:133]
	s_mov_b32 m0, s77
	ds_read_b128 v[212:215], v152
	ds_read_b128 v[216:219], v152 offset:1024
	ds_read_b128 v[220:223], v152 offset:2048
	ds_read_b128 v[224:227], v152 offset:3072
	global_load_lds_dwordx4 v[148:149], off
	v_lshl_add_u64 v[198:199], s[46:47], 0, v[136:137]
	s_add_i32 m0, s77, 0x2000
	s_nop 0
	global_load_lds_dwordx4 v[198:199], off
	s_barrier
	s_waitcnt lgkmcnt(0)
	s_setprio 1
	v_mfma_f32_16x16x32_bf16 v[118:121], v[212:215], v[174:177], v[118:121]
	v_mfma_f32_16x16x32_bf16 v[110:113], v[220:223], v[174:177], v[110:113]
	v_mfma_f32_16x16x32_bf16 v[102:105], v[212:215], v[182:185], v[102:105]
	v_mfma_f32_16x16x32_bf16 v[94:97], v[220:223], v[182:185], v[94:97]
	v_mfma_f32_16x16x32_bf16 v[86:89], v[212:215], v[190:193], v[86:89]
	v_mfma_f32_16x16x32_bf16 v[78:81], v[220:223], v[190:193], v[78:81]
	v_mfma_f32_16x16x32_bf16 v[70:73], v[212:215], v[204:207], v[70:73]
	v_mfma_f32_16x16x32_bf16 v[66:69], v[220:223], v[204:207], v[66:69]
	v_mfma_f32_16x16x32_bf16 v[118:121], v[216:219], v[178:181], v[118:121]
	v_mfma_f32_16x16x32_bf16 v[110:113], v[224:227], v[178:181], v[110:113]
	v_mfma_f32_16x16x32_bf16 v[102:105], v[216:219], v[186:189], v[102:105]
	v_mfma_f32_16x16x32_bf16 v[94:97], v[224:227], v[186:189], v[94:97]
	v_mfma_f32_16x16x32_bf16 v[86:89], v[216:219], v[194:197], v[86:89]
	v_mfma_f32_16x16x32_bf16 v[78:81], v[224:227], v[194:197], v[78:81]
	v_mfma_f32_16x16x32_bf16 v[70:73], v[216:219], v[208:211], v[70:73]
	v_mfma_f32_16x16x32_bf16 v[66:69], v[224:227], v[208:211], v[66:69]
	s_setprio 0
	s_barrier
	s_mov_b32 m0, s34
	v_lshl_add_u64 v[228:229], s[50:51], 0, v[130:131]
	ds_read_b128 v[174:177], v151 offset:16384
	ds_read_b128 v[178:181], v151 offset:17408
	ds_read_b128 v[182:185], v151 offset:18432
	ds_read_b128 v[186:189], v151 offset:19456
	ds_read_b128 v[190:193], v151 offset:20480
	ds_read_b128 v[194:197], v151 offset:21504
	ds_read_b128 v[204:207], v151 offset:22528
	ds_read_b128 v[208:211], v151 offset:23552
	global_load_lds_dwordx4 v[228:229], off
	v_lshl_add_u64 v[230:231], s[50:51], 0, v[134:135]
	s_mov_b32 m0, s35
	s_nop 0
	global_load_lds_dwordx4 v[230:231], off
	s_barrier
	s_waitcnt lgkmcnt(0)
	s_setprio 1
	v_mfma_f32_16x16x32_bf16 v[62:65], v[158:161], v[174:177], v[62:65]
	v_mfma_f32_16x16x32_bf16 v[58:61], v[166:169], v[174:177], v[58:61]
	v_mfma_f32_16x16x32_bf16 v[54:57], v[158:161], v[182:185], v[54:57]
	v_mfma_f32_16x16x32_bf16 v[46:49], v[166:169], v[182:185], v[46:49]
	v_mfma_f32_16x16x32_bf16 v[38:41], v[158:161], v[190:193], v[38:41]
	v_mfma_f32_16x16x32_bf16 v[30:33], v[166:169], v[190:193], v[30:33]
	v_mfma_f32_16x16x32_bf16 v[22:25], v[158:161], v[204:207], v[22:25]
	v_mfma_f32_16x16x32_bf16 v[14:17], v[166:169], v[204:207], v[14:17]
	v_mfma_f32_16x16x32_bf16 v[62:65], v[162:165], v[178:181], v[62:65]
	v_mfma_f32_16x16x32_bf16 v[58:61], v[170:173], v[178:181], v[58:61]
	v_mfma_f32_16x16x32_bf16 v[54:57], v[162:165], v[186:189], v[54:57]
	v_mfma_f32_16x16x32_bf16 v[46:49], v[170:173], v[186:189], v[46:49]
	v_mfma_f32_16x16x32_bf16 v[38:41], v[162:165], v[194:197], v[38:41]
	v_mfma_f32_16x16x32_bf16 v[30:33], v[170:173], v[194:197], v[30:33]
	v_mfma_f32_16x16x32_bf16 v[22:25], v[162:165], v[208:211], v[22:25]
	v_mfma_f32_16x16x32_bf16 v[14:17], v[170:173], v[208:211], v[14:17]
	s_setprio 0
	s_barrier
	s_add_u32 s78, s46, 0x80000
	s_addc_u32 s79, s47, 0
	s_add_i32 s77, s66, s33
	v_lshl_add_u64 v[158:159], s[78:79], 0, v[132:133]
	s_mov_b32 m0, s77
	s_nop 0
	global_load_lds_dwordx4 v[158:159], off
	v_lshl_add_u64 v[158:159], s[78:79], 0, v[136:137]
	s_add_i32 m0, s77, 0x2000
	s_nop 0
	global_load_lds_dwordx4 v[158:159], off
	s_waitcnt vmcnt(6)
	s_barrier
	s_setprio 1
	v_mfma_f32_16x16x32_bf16 v[50:53], v[212:215], v[174:177], v[50:53]
	v_mfma_f32_16x16x32_bf16 v[42:45], v[220:223], v[174:177], v[42:45]
	v_mfma_f32_16x16x32_bf16 v[34:37], v[212:215], v[182:185], v[34:37]
	v_mfma_f32_16x16x32_bf16 v[26:29], v[220:223], v[182:185], v[26:29]
	v_mfma_f32_16x16x32_bf16 v[18:21], v[212:215], v[190:193], v[18:21]
	v_mfma_f32_16x16x32_bf16 v[10:13], v[220:223], v[190:193], v[10:13]
	v_mfma_f32_16x16x32_bf16 v[6:9], v[212:215], v[204:207], v[6:9]
	v_mfma_f32_16x16x32_bf16 v[2:5], v[220:223], v[204:207], v[2:5]
	v_mfma_f32_16x16x32_bf16 v[50:53], v[216:219], v[178:181], v[50:53]
	v_mfma_f32_16x16x32_bf16 v[42:45], v[224:227], v[178:181], v[42:45]
	v_mfma_f32_16x16x32_bf16 v[34:37], v[216:219], v[186:189], v[34:37]
	v_mfma_f32_16x16x32_bf16 v[26:29], v[224:227], v[186:189], v[26:29]
	v_mfma_f32_16x16x32_bf16 v[18:21], v[216:219], v[194:197], v[18:21]
	v_mfma_f32_16x16x32_bf16 v[10:13], v[224:227], v[194:197], v[10:13]
	v_mfma_f32_16x16x32_bf16 v[6:9], v[216:219], v[208:211], v[6:9]
	v_mfma_f32_16x16x32_bf16 v[2:5], v[224:227], v[208:211], v[2:5]
	s_setprio 0
	s_barrier
	s_add_i32 s77, 0, 0x18000
	v_add_u32_e32 v153, s77, v155
	ds_read_b128 v[158:161], v153
	ds_read_b128 v[162:165], v153 offset:1024
	ds_read_b128 v[166:169], v153 offset:2048
	ds_read_b128 v[170:173], v153 offset:3072
	s_add_u32 s50, s50, 0x80000
	s_addc_u32 s51, s51, 0
	s_mov_b32 m0, s43
	v_lshl_add_u64 v[212:213], s[50:51], 0, v[130:131]
	ds_read_b128 v[174:177], v151 offset:32768
	ds_read_b128 v[178:181], v151 offset:33792
	ds_read_b128 v[182:185], v151 offset:34816
	ds_read_b128 v[186:189], v151 offset:35840
	ds_read_b128 v[190:193], v151 offset:36864
	ds_read_b128 v[194:197], v151 offset:37888
	ds_read_b128 v[204:207], v151 offset:38912
	ds_read_b128 v[208:211], v151 offset:39936
	global_load_lds_dwordx4 v[212:213], off
	v_lshl_add_u64 v[212:213], s[50:51], 0, v[134:135]
	s_mov_b32 m0, s60
	s_nop 0
	global_load_lds_dwordx4 v[212:213], off
	s_waitcnt lgkmcnt(8)
	s_barrier
	s_waitcnt lgkmcnt(0)
	s_setprio 1
	v_mfma_f32_16x16x32_bf16 v[126:129], v[158:161], v[174:177], v[126:129]
	v_mfma_f32_16x16x32_bf16 v[122:125], v[166:169], v[174:177], v[122:125]
	v_mfma_f32_16x16x32_bf16 v[114:117], v[158:161], v[182:185], v[114:117]
	v_mfma_f32_16x16x32_bf16 v[106:109], v[166:169], v[182:185], v[106:109]
	v_mfma_f32_16x16x32_bf16 v[98:101], v[158:161], v[190:193], v[98:101]
	v_mfma_f32_16x16x32_bf16 v[90:93], v[166:169], v[190:193], v[90:93]
	v_mfma_f32_16x16x32_bf16 v[82:85], v[158:161], v[204:207], v[82:85]
	v_mfma_f32_16x16x32_bf16 v[74:77], v[166:169], v[204:207], v[74:77]
	v_mfma_f32_16x16x32_bf16 v[126:129], v[162:165], v[178:181], v[126:129]
	v_mfma_f32_16x16x32_bf16 v[122:125], v[170:173], v[178:181], v[122:125]
	v_mfma_f32_16x16x32_bf16 v[114:117], v[162:165], v[186:189], v[114:117]
	v_mfma_f32_16x16x32_bf16 v[106:109], v[170:173], v[186:189], v[106:109]
	v_mfma_f32_16x16x32_bf16 v[98:101], v[162:165], v[194:197], v[98:101]
	v_mfma_f32_16x16x32_bf16 v[90:93], v[170:173], v[194:197], v[90:93]
	v_mfma_f32_16x16x32_bf16 v[82:85], v[162:165], v[208:211], v[82:85]
	v_mfma_f32_16x16x32_bf16 v[74:77], v[170:173], v[208:211], v[74:77]
	s_setprio 0
	s_barrier
	s_add_i32 s50, 0, 0x1c000
	s_add_i32 s51, s77, s33
	v_add_u32_e32 v153, s50, v155
	v_lshl_add_u64 v[148:149], v[148:149], 0, s[10:11]
	s_mov_b32 m0, s51
	ds_read_b128 v[212:215], v153
	ds_read_b128 v[216:219], v153 offset:1024
	ds_read_b128 v[220:223], v153 offset:2048
	ds_read_b128 v[224:227], v153 offset:3072
	global_load_lds_dwordx4 v[148:149], off
	v_lshl_add_u64 v[148:149], v[198:199], 0, s[10:11]
	s_add_i32 m0, s51, 0x2000
	s_nop 0
	global_load_lds_dwordx4 v[148:149], off
	s_barrier
	s_waitcnt lgkmcnt(0)
	s_setprio 1
	v_mfma_f32_16x16x32_bf16 v[118:121], v[212:215], v[174:177], v[118:121]
	v_mfma_f32_16x16x32_bf16 v[110:113], v[220:223], v[174:177], v[110:113]
	v_mfma_f32_16x16x32_bf16 v[102:105], v[212:215], v[182:185], v[102:105]
	v_mfma_f32_16x16x32_bf16 v[94:97], v[220:223], v[182:185], v[94:97]
	v_mfma_f32_16x16x32_bf16 v[86:89], v[212:215], v[190:193], v[86:89]
	v_mfma_f32_16x16x32_bf16 v[78:81], v[220:223], v[190:193], v[78:81]
	v_mfma_f32_16x16x32_bf16 v[70:73], v[212:215], v[204:207], v[70:73]
	v_mfma_f32_16x16x32_bf16 v[66:69], v[220:223], v[204:207], v[66:69]
	v_mfma_f32_16x16x32_bf16 v[118:121], v[216:219], v[178:181], v[118:121]
	v_mfma_f32_16x16x32_bf16 v[110:113], v[224:227], v[178:181], v[110:113]
	v_mfma_f32_16x16x32_bf16 v[102:105], v[216:219], v[186:189], v[102:105]
	v_mfma_f32_16x16x32_bf16 v[94:97], v[224:227], v[186:189], v[94:97]
	v_mfma_f32_16x16x32_bf16 v[86:89], v[216:219], v[194:197], v[86:89]
	v_mfma_f32_16x16x32_bf16 v[78:81], v[224:227], v[194:197], v[78:81]
	v_mfma_f32_16x16x32_bf16 v[70:73], v[216:219], v[208:211], v[70:73]
	v_mfma_f32_16x16x32_bf16 v[66:69], v[224:227], v[208:211], v[66:69]
	s_setprio 0
	s_barrier
	s_mov_b32 m0, s62
	v_lshl_add_u64 v[148:149], v[228:229], 0, s[10:11]
	ds_read_b128 v[174:177], v151 offset:49152
	ds_read_b128 v[178:181], v151 offset:50176
	ds_read_b128 v[182:185], v151 offset:51200
	ds_read_b128 v[186:189], v151 offset:52224
	ds_read_b128 v[190:193], v151 offset:53248
	ds_read_b128 v[194:197], v151 offset:54272
	ds_read_b128 v[204:207], v151 offset:55296
	ds_read_b128 v[208:211], v151 offset:56320
	global_load_lds_dwordx4 v[148:149], off
	v_lshl_add_u64 v[148:149], v[230:231], 0, s[10:11]
	s_mov_b32 m0, s63
	s_nop 0
	global_load_lds_dwordx4 v[148:149], off
	s_barrier
	s_waitcnt lgkmcnt(0)
	s_setprio 1
	v_mfma_f32_16x16x32_bf16 v[62:65], v[158:161], v[174:177], v[62:65]
	v_mfma_f32_16x16x32_bf16 v[58:61], v[166:169], v[174:177], v[58:61]
	v_mfma_f32_16x16x32_bf16 v[54:57], v[158:161], v[182:185], v[54:57]
	v_mfma_f32_16x16x32_bf16 v[46:49], v[166:169], v[182:185], v[46:49]
	v_mfma_f32_16x16x32_bf16 v[38:41], v[158:161], v[190:193], v[38:41]
	v_mfma_f32_16x16x32_bf16 v[30:33], v[166:169], v[190:193], v[30:33]
	v_mfma_f32_16x16x32_bf16 v[22:25], v[158:161], v[204:207], v[22:25]
	v_mfma_f32_16x16x32_bf16 v[14:17], v[166:169], v[204:207], v[14:17]
	v_mfma_f32_16x16x32_bf16 v[62:65], v[162:165], v[178:181], v[62:65]
	v_mfma_f32_16x16x32_bf16 v[58:61], v[170:173], v[178:181], v[58:61]
	v_mfma_f32_16x16x32_bf16 v[54:57], v[162:165], v[186:189], v[54:57]
	v_mfma_f32_16x16x32_bf16 v[46:49], v[170:173], v[186:189], v[46:49]
	v_mfma_f32_16x16x32_bf16 v[38:41], v[162:165], v[194:197], v[38:41]
	v_mfma_f32_16x16x32_bf16 v[30:33], v[170:173], v[194:197], v[30:33]
	v_mfma_f32_16x16x32_bf16 v[22:25], v[162:165], v[208:211], v[22:25]
	v_mfma_f32_16x16x32_bf16 v[14:17], v[170:173], v[208:211], v[14:17]
	s_setprio 0
	s_barrier
	s_add_u32 s46, s46, 0x80080
	s_addc_u32 s47, s47, 0
	s_add_i32 s50, s50, s33
	v_lshl_add_u64 v[148:149], s[46:47], 0, v[132:133]
	s_mov_b32 m0, s50
	s_nop 0
	global_load_lds_dwordx4 v[148:149], off
	v_lshl_add_u64 v[148:149], s[46:47], 0, v[136:137]
	s_add_i32 m0, s50, 0x2000
	s_nop 0
	global_load_lds_dwordx4 v[148:149], off
	s_waitcnt vmcnt(6)
	s_barrier
	s_setprio 1
	v_mfma_f32_16x16x32_bf16 v[50:53], v[212:215], v[174:177], v[50:53]
	v_mfma_f32_16x16x32_bf16 v[42:45], v[220:223], v[174:177], v[42:45]
	v_mfma_f32_16x16x32_bf16 v[34:37], v[212:215], v[182:185], v[34:37]
	v_mfma_f32_16x16x32_bf16 v[26:29], v[220:223], v[182:185], v[26:29]
	v_mfma_f32_16x16x32_bf16 v[18:21], v[212:215], v[190:193], v[18:21]
	v_mfma_f32_16x16x32_bf16 v[10:13], v[220:223], v[190:193], v[10:13]
	v_mfma_f32_16x16x32_bf16 v[6:9], v[212:215], v[204:207], v[6:9]
	v_mfma_f32_16x16x32_bf16 v[2:5], v[220:223], v[204:207], v[2:5]
	v_mfma_f32_16x16x32_bf16 v[50:53], v[216:219], v[178:181], v[50:53]
	v_mfma_f32_16x16x32_bf16 v[42:45], v[224:227], v[178:181], v[42:45]
	v_mfma_f32_16x16x32_bf16 v[34:37], v[216:219], v[186:189], v[34:37]
	v_mfma_f32_16x16x32_bf16 v[26:29], v[224:227], v[186:189], v[26:29]
	v_mfma_f32_16x16x32_bf16 v[18:21], v[216:219], v[194:197], v[18:21]
	v_mfma_f32_16x16x32_bf16 v[10:13], v[224:227], v[194:197], v[10:13]
	v_mfma_f32_16x16x32_bf16 v[6:9], v[216:219], v[208:211], v[6:9]
	v_mfma_f32_16x16x32_bf16 v[2:5], v[224:227], v[208:211], v[2:5]
	s_setprio 0
	s_barrier
	s_add_i32 s76, s76, 2
	s_add_u32 s44, s44, 0x100
	s_addc_u32 s45, s45, 0
	s_add_u32 s74, s74, 0x100
	s_addc_u32 s75, s75, 0
	s_cmp_gt_u32 s76, 29
	s_cbranch_scc0 .LBB0_365
	v_lshl_add_u32 v158, s42, 8, v157
	v_lshl_or_b32 v148, s71, 8, v154
	v_ashrrev_i32_e32 v159, 31, v158
	v_ashrrev_i32_e32 v149, 31, v148
	v_lshlrev_b64 v[160:161], 12, v[158:159]
	v_lshl_add_u64 v[160:161], s[8:9], 0, v[160:161]
	v_lshlrev_b64 v[162:163], 1, v[148:149]
	v_lshl_add_u64 v[148:149], v[160:161], 0, v[162:163]
	v_cvt_pk_bf16_f32 v126, v126, v127
	v_cvt_pk_bf16_f32 v127, v128, v129
	v_cvt_pk_bf16_f32 v128, v122, v123
	v_cvt_pk_bf16_f32 v129, v124, v125
	global_store_dwordx4 v[148:149], v[126:129], off
	v_cvt_pk_bf16_f32 v118, v118, v119
	v_cvt_pk_bf16_f32 v119, v120, v121
	v_cvt_pk_bf16_f32 v120, v110, v111
	v_or_b32_e32 v110, 16, v158
	v_ashrrev_i32_e32 v111, 31, v110
	v_lshlrev_b64 v[110:111], 12, v[110:111]
	v_lshl_add_u64 v[110:111], s[8:9], 0, v[110:111]
	v_cvt_pk_bf16_f32 v121, v112, v113
	global_store_dwordx4 v[148:149], v[118:121], off offset:256
	s_mov_b32 s71, s26
	s_mov_b32 s42, s36
	v_lshl_add_u64 v[118:119], v[110:111], 0, v[162:163]
	v_cvt_pk_bf16_f32 v110, v114, v115
	v_cvt_pk_bf16_f32 v111, v116, v117
	v_cvt_pk_bf16_f32 v112, v106, v107
	v_cvt_pk_bf16_f32 v113, v108, v109
	global_store_dwordx4 v[118:119], v[110:113], off
	v_cvt_pk_bf16_f32 v102, v102, v103
	v_cvt_pk_bf16_f32 v103, v104, v105
	v_cvt_pk_bf16_f32 v104, v94, v95
	v_or_b32_e32 v94, 32, v158
	v_ashrrev_i32_e32 v95, 31, v94
	v_lshlrev_b64 v[94:95], 12, v[94:95]
	v_lshl_add_u64 v[94:95], s[8:9], 0, v[94:95]
	v_cvt_pk_bf16_f32 v105, v96, v97
	global_store_dwordx4 v[118:119], v[102:105], off offset:256
	s_mov_b64 s[46:47], s[40:41]
	s_mov_b64 s[44:45], s[38:39]
	v_lshl_add_u64 v[102:103], v[94:95], 0, v[162:163]
	v_cvt_pk_bf16_f32 v94, v98, v99
	v_cvt_pk_bf16_f32 v95, v100, v101
	v_cvt_pk_bf16_f32 v96, v90, v91
	v_cvt_pk_bf16_f32 v97, v92, v93
	global_store_dwordx4 v[102:103], v[94:97], off
	v_cvt_pk_bf16_f32 v86, v86, v87
	v_cvt_pk_bf16_f32 v87, v88, v89
	v_cvt_pk_bf16_f32 v88, v78, v79
	v_or_b32_e32 v78, 48, v158
	v_ashrrev_i32_e32 v79, 31, v78
	v_lshlrev_b64 v[78:79], 12, v[78:79]
	v_lshl_add_u64 v[78:79], s[8:9], 0, v[78:79]
	v_cvt_pk_bf16_f32 v89, v80, v81
	global_store_dwordx4 v[102:103], v[86:89], off offset:256
	s_nop 1
	v_lshl_add_u64 v[86:87], v[78:79], 0, v[162:163]
	v_cvt_pk_bf16_f32 v78, v82, v83
	v_cvt_pk_bf16_f32 v79, v84, v85
	v_cvt_pk_bf16_f32 v80, v74, v75
	v_cvt_pk_bf16_f32 v81, v76, v77
	global_store_dwordx4 v[86:87], v[78:81], off
	v_cvt_pk_bf16_f32 v70, v70, v71
	v_cvt_pk_bf16_f32 v71, v72, v73
	v_cvt_pk_bf16_f32 v72, v66, v67
	v_cvt_pk_bf16_f32 v73, v68, v69
	global_store_dwordx4 v[86:87], v[70:73], off offset:256
	v_cvt_pk_bf16_f32 v62, v62, v63
	v_cvt_pk_bf16_f32 v63, v64, v65
	v_cvt_pk_bf16_f32 v64, v58, v59
	v_add_co_u32_e32 v58, vcc, s67, v148
	v_lshl_add_u64 v[66:67], v[148:149], 0, s[6:7]
	s_nop 0
	v_addc_co_u32_e32 v59, vcc, 0, v149, vcc
	v_cvt_pk_bf16_f32 v65, v60, v61
	global_store_dwordx4 v[58:59], v[62:65], off
	v_cvt_pk_bf16_f32 v50, v50, v51
	v_cvt_pk_bf16_f32 v51, v52, v53
	v_cvt_pk_bf16_f32 v52, v42, v43
	v_cvt_pk_bf16_f32 v53, v44, v45
	global_store_dwordx4 v[66:67], v[50:53], off offset:256
	v_cvt_pk_bf16_f32 v42, v54, v55
	v_cvt_pk_bf16_f32 v43, v56, v57
	v_cvt_pk_bf16_f32 v44, v46, v47
	v_add_co_u32_e32 v46, vcc, s68, v148
	s_nop 0
	v_lshl_add_u64 v[50:51], v[148:149], 0, s[16:17]
	v_addc_co_u32_e32 v47, vcc, 0, v149, vcc
	v_cvt_pk_bf16_f32 v45, v48, v49
	global_store_dwordx4 v[46:47], v[42:45], off
	v_cvt_pk_bf16_f32 v34, v34, v35
	v_cvt_pk_bf16_f32 v35, v36, v37
	v_cvt_pk_bf16_f32 v36, v26, v27
	v_cvt_pk_bf16_f32 v37, v28, v29
	global_store_dwordx4 v[50:51], v[34:37], off offset:256
	v_cvt_pk_bf16_f32 v26, v38, v39
	v_cvt_pk_bf16_f32 v27, v40, v41
	v_cvt_pk_bf16_f32 v28, v30, v31
	v_add_co_u32_e32 v30, vcc, s69, v148
	s_nop 0
	v_lshl_add_u64 v[34:35], v[148:149], 0, s[18:19]
	v_addc_co_u32_e32 v31, vcc, 0, v149, vcc
	v_cvt_pk_bf16_f32 v29, v32, v33
	global_store_dwordx4 v[30:31], v[26:29], off
	v_cvt_pk_bf16_f32 v18, v18, v19
	v_cvt_pk_bf16_f32 v19, v20, v21
	v_cvt_pk_bf16_f32 v20, v10, v11
	v_cvt_pk_bf16_f32 v21, v12, v13
	global_store_dwordx4 v[34:35], v[18:21], off offset:256
	v_cvt_pk_bf16_f32 v10, v22, v23
	v_cvt_pk_bf16_f32 v11, v24, v25
	v_cvt_pk_bf16_f32 v12, v14, v15
	v_add_co_u32_e32 v14, vcc, s70, v148
	s_nop 0
	v_lshl_add_u64 v[18:19], v[148:149], 0, s[24:25]
	v_addc_co_u32_e32 v15, vcc, 0, v149, vcc
	s_and_b64 vcc, exec, s[0:1]
	v_cvt_pk_bf16_f32 v13, v16, v17
	global_store_dwordx4 v[14:15], v[10:13], off
	v_cvt_pk_bf16_f32 v6, v6, v7
	v_cvt_pk_bf16_f32 v7, v8, v9
	v_cvt_pk_bf16_f32 v8, v2, v3
	v_cvt_pk_bf16_f32 v9, v4, v5
	global_store_dwordx4 v[18:19], v[6:9], off offset:256
	s_cbranch_vccz .LBB0_358
	s_waitcnt vmcnt(0)
	s_cmpk_gt_u32 s3, 0xff
	s_cbranch_scc1 .LBB0_369
	s_barrier

.LBB0_710:
	s_add_u32 s44, s42, 0xfffe0080
	s_addc_u32 s45, s43, -1
	s_add_i32 s76, 0, 0x10000
	v_add_u32_e32 v142, s76, v177
	ds_read_b128 v[130:133], v142
	ds_read_b128 v[134:137], v142 offset:1024
	ds_read_b128 v[138:141], v142 offset:2048
	ds_read_b128 v[142:145], v142 offset:3072
	s_cmp_eq_u32 s75, 4
	s_cselect_b32 s47, s27, s45
	s_cselect_b32 s46, s41, s44
	s_cselect_b32 s45, s25, s74
	s_cselect_b32 s44, s72, s73
	v_lshl_add_u64 v[198:199], s[42:43], 0, v[158:159]
	s_add_i32 m0, s66, 0xc000
	ds_read_b128 v[166:169], v156
	ds_read_b128 v[178:181], v156 offset:1024
	ds_read_b128 v[182:185], v156 offset:2048
	ds_read_b128 v[186:189], v156 offset:3072
	ds_read_b128 v[190:193], v156 offset:4096
	ds_read_b128 v[194:197], v156 offset:5120
	ds_read_b128 v[202:205], v156 offset:6144
	ds_read_b128 v[206:209], v156 offset:7168
	global_load_lds_dwordx4 v[198:199], off
	v_lshl_add_u64 v[198:199], s[42:43], 0, v[160:161]
	s_add_i32 m0, s66, 0xe000
	s_nop 0
	global_load_lds_dwordx4 v[198:199], off
	s_waitcnt lgkmcnt(8)
	s_barrier
	s_waitcnt lgkmcnt(0)
	s_setprio 1
	v_mfma_f32_16x16x32_bf16 v[126:129], v[130:133], v[166:169], v[126:129]
	v_mfma_f32_16x16x32_bf16 v[122:125], v[138:141], v[166:169], v[122:125]
	v_mfma_f32_16x16x32_bf16 v[110:113], v[130:133], v[182:185], v[110:113]
	v_mfma_f32_16x16x32_bf16 v[106:109], v[138:141], v[182:185], v[106:109]
	v_mfma_f32_16x16x32_bf16 v[94:97], v[130:133], v[190:193], v[94:97]
	v_mfma_f32_16x16x32_bf16 v[90:93], v[138:141], v[190:193], v[90:93]
	v_mfma_f32_16x16x32_bf16 v[78:81], v[130:133], v[202:205], v[78:81]
	v_mfma_f32_16x16x32_bf16 v[74:77], v[138:141], v[202:205], v[74:77]
	v_mfma_f32_16x16x32_bf16 v[126:129], v[134:137], v[178:181], v[126:129]
	v_mfma_f32_16x16x32_bf16 v[122:125], v[142:145], v[178:181], v[122:125]
	v_mfma_f32_16x16x32_bf16 v[110:113], v[134:137], v[186:189], v[110:113]
	v_mfma_f32_16x16x32_bf16 v[106:109], v[142:145], v[186:189], v[106:109]
	v_mfma_f32_16x16x32_bf16 v[94:97], v[134:137], v[194:197], v[94:97]
	v_mfma_f32_16x16x32_bf16 v[90:93], v[142:145], v[194:197], v[90:93]
	v_mfma_f32_16x16x32_bf16 v[78:81], v[134:137], v[206:209], v[78:81]
	v_mfma_f32_16x16x32_bf16 v[74:77], v[142:145], v[206:209], v[74:77]
	s_setprio 0
	s_barrier
	s_add_i32 s78, 0, 0x14000
	v_add_u32_e32 v198, s78, v177
	s_add_i32 s76, s76, s65
	ds_read_b128 v[210:213], v198
	ds_read_b128 v[214:217], v198 offset:1024
	ds_read_b128 v[218:221], v198 offset:2048
	ds_read_b128 v[222:225], v198 offset:3072
	v_lshl_add_u64 v[198:199], s[44:45], 0, v[150:151]
	s_mov_b32 m0, s76
	v_lshl_add_u64 v[226:227], s[44:45], 0, v[154:155]
	global_load_lds_dwordx4 v[198:199], off
	s_add_i32 m0, s76, 0x2000
	s_nop 0
	global_load_lds_dwordx4 v[226:227], off
	s_barrier
	s_waitcnt lgkmcnt(0)
	s_setprio 1
	v_mfma_f32_16x16x32_bf16 v[118:121], v[210:213], v[166:169], v[118:121]
	v_mfma_f32_16x16x32_bf16 v[114:117], v[218:221], v[166:169], v[114:117]
	v_mfma_f32_16x16x32_bf16 v[102:105], v[210:213], v[182:185], v[102:105]
	v_mfma_f32_16x16x32_bf16 v[98:101], v[218:221], v[182:185], v[98:101]
	v_mfma_f32_16x16x32_bf16 v[86:89], v[210:213], v[190:193], v[86:89]
	v_mfma_f32_16x16x32_bf16 v[82:85], v[218:221], v[190:193], v[82:85]
	v_mfma_f32_16x16x32_bf16 v[70:73], v[210:213], v[202:205], v[70:73]
	v_mfma_f32_16x16x32_bf16 v[66:69], v[218:221], v[202:205], v[66:69]
	v_mfma_f32_16x16x32_bf16 v[118:121], v[214:217], v[178:181], v[118:121]
	v_mfma_f32_16x16x32_bf16 v[114:117], v[222:225], v[178:181], v[114:117]
	v_mfma_f32_16x16x32_bf16 v[102:105], v[214:217], v[186:189], v[102:105]
	v_mfma_f32_16x16x32_bf16 v[98:101], v[222:225], v[186:189], v[98:101]
	v_mfma_f32_16x16x32_bf16 v[86:89], v[214:217], v[194:197], v[86:89]
	v_mfma_f32_16x16x32_bf16 v[82:85], v[222:225], v[194:197], v[82:85]
	v_mfma_f32_16x16x32_bf16 v[70:73], v[214:217], v[206:209], v[70:73]
	v_mfma_f32_16x16x32_bf16 v[66:69], v[222:225], v[206:209], v[66:69]
	s_setprio 0
	s_barrier
	s_mov_b32 m0, s66
	v_lshl_add_u64 v[228:229], s[46:47], 0, v[148:149]
	ds_read_b128 v[166:169], v156 offset:16384
	ds_read_b128 v[178:181], v156 offset:17408
	ds_read_b128 v[182:185], v156 offset:18432
	ds_read_b128 v[186:189], v156 offset:19456
	ds_read_b128 v[190:193], v156 offset:20480
	ds_read_b128 v[194:197], v156 offset:21504
	ds_read_b128 v[202:205], v156 offset:22528
	ds_read_b128 v[206:209], v156 offset:23552
	global_load_lds_dwordx4 v[228:229], off
	v_lshl_add_u64 v[230:231], s[46:47], 0, v[152:153]
	s_mov_b32 m0, s67
	s_nop 0
	global_load_lds_dwordx4 v[230:231], off
	s_barrier
	s_waitcnt lgkmcnt(0)
	s_setprio 1
	v_mfma_f32_16x16x32_bf16 v[62:65], v[130:133], v[166:169], v[62:65]
	v_mfma_f32_16x16x32_bf16 v[58:61], v[138:141], v[166:169], v[58:61]
	v_mfma_f32_16x16x32_bf16 v[46:49], v[130:133], v[182:185], v[46:49]
	v_mfma_f32_16x16x32_bf16 v[42:45], v[138:141], v[182:185], v[42:45]
	v_mfma_f32_16x16x32_bf16 v[30:33], v[130:133], v[190:193], v[30:33]
	v_mfma_f32_16x16x32_bf16 v[26:29], v[138:141], v[190:193], v[26:29]
	v_mfma_f32_16x16x32_bf16 v[14:17], v[130:133], v[202:205], v[14:17]
	v_mfma_f32_16x16x32_bf16 v[10:13], v[138:141], v[202:205], v[10:13]
	v_mfma_f32_16x16x32_bf16 v[62:65], v[134:137], v[178:181], v[62:65]
	v_mfma_f32_16x16x32_bf16 v[58:61], v[142:145], v[178:181], v[58:61]
	v_mfma_f32_16x16x32_bf16 v[46:49], v[134:137], v[186:189], v[46:49]
	v_mfma_f32_16x16x32_bf16 v[42:45], v[142:145], v[186:189], v[42:45]
	v_mfma_f32_16x16x32_bf16 v[30:33], v[134:137], v[194:197], v[30:33]
	v_mfma_f32_16x16x32_bf16 v[26:29], v[142:145], v[194:197], v[26:29]
	v_mfma_f32_16x16x32_bf16 v[14:17], v[134:137], v[206:209], v[14:17]
	v_mfma_f32_16x16x32_bf16 v[10:13], v[142:145], v[206:209], v[10:13]
	s_setprio 0
	s_barrier
	s_add_u32 s76, s44, 0x20000
	s_addc_u32 s77, s45, 0
	s_add_i32 s78, s78, s65
	v_lshl_add_u64 v[130:131], s[76:77], 0, v[150:151]
	s_mov_b32 m0, s78
	s_nop 0
	global_load_lds_dwordx4 v[130:131], off
	v_lshl_add_u64 v[130:131], s[76:77], 0, v[154:155]
	s_add_i32 m0, s78, 0x2000
	s_nop 0
	global_load_lds_dwordx4 v[130:131], off
	s_waitcnt vmcnt(6)
	s_barrier
	s_setprio 1
	v_mfma_f32_16x16x32_bf16 v[54:57], v[210:213], v[166:169], v[54:57]
	v_mfma_f32_16x16x32_bf16 v[50:53], v[218:221], v[166:169], v[50:53]
	v_mfma_f32_16x16x32_bf16 v[38:41], v[210:213], v[182:185], v[38:41]
	v_mfma_f32_16x16x32_bf16 v[34:37], v[218:221], v[182:185], v[34:37]
	v_mfma_f32_16x16x32_bf16 v[22:25], v[210:213], v[190:193], v[22:25]
	v_mfma_f32_16x16x32_bf16 v[18:21], v[218:221], v[190:193], v[18:21]
	v_mfma_f32_16x16x32_bf16 v[6:9], v[210:213], v[202:205], v[6:9]
	v_mfma_f32_16x16x32_bf16 v[2:5], v[218:221], v[202:205], v[2:5]
	v_mfma_f32_16x16x32_bf16 v[54:57], v[214:217], v[178:181], v[54:57]
	v_mfma_f32_16x16x32_bf16 v[50:53], v[222:225], v[178:181], v[50:53]
	v_mfma_f32_16x16x32_bf16 v[38:41], v[214:217], v[186:189], v[38:41]
	v_mfma_f32_16x16x32_bf16 v[34:37], v[222:225], v[186:189], v[34:37]
	v_mfma_f32_16x16x32_bf16 v[22:25], v[214:217], v[194:197], v[22:25]
	v_mfma_f32_16x16x32_bf16 v[18:21], v[222:225], v[194:197], v[18:21]
	v_mfma_f32_16x16x32_bf16 v[6:9], v[214:217], v[206:209], v[6:9]
	v_mfma_f32_16x16x32_bf16 v[2:5], v[222:225], v[206:209], v[2:5]
	s_setprio 0
	s_barrier
	s_add_i32 s76, 0, 0x18000
	v_add_u32_e32 v142, s76, v177
	ds_read_b128 v[130:133], v142
	ds_read_b128 v[134:137], v142 offset:1024
	ds_read_b128 v[138:141], v142 offset:2048
	ds_read_b128 v[142:145], v142 offset:3072
	s_add_u32 s46, s46, 0x20000
	s_addc_u32 s47, s47, 0
	s_mov_b32 m0, s68
	v_lshl_add_u64 v[210:211], s[46:47], 0, v[148:149]
	ds_read_b128 v[166:169], v156 offset:32768
	ds_read_b128 v[178:181], v156 offset:33792
	ds_read_b128 v[182:185], v156 offset:34816
	ds_read_b128 v[186:189], v156 offset:35840
	ds_read_b128 v[190:193], v156 offset:36864
	ds_read_b128 v[194:197], v156 offset:37888
	ds_read_b128 v[202:205], v156 offset:38912
	ds_read_b128 v[206:209], v156 offset:39936
	global_load_lds_dwordx4 v[210:211], off
	v_lshl_add_u64 v[210:211], s[46:47], 0, v[152:153]
	s_mov_b32 m0, s69
	s_nop 0
	global_load_lds_dwordx4 v[210:211], off
	s_waitcnt lgkmcnt(8)
	s_barrier
	s_waitcnt lgkmcnt(0)
	s_setprio 1
	v_mfma_f32_16x16x32_bf16 v[126:129], v[130:133], v[166:169], v[126:129]
	v_mfma_f32_16x16x32_bf16 v[122:125], v[138:141], v[166:169], v[122:125]
	v_mfma_f32_16x16x32_bf16 v[110:113], v[130:133], v[182:185], v[110:113]
	v_mfma_f32_16x16x32_bf16 v[106:109], v[138:141], v[182:185], v[106:109]
	v_mfma_f32_16x16x32_bf16 v[94:97], v[130:133], v[190:193], v[94:97]
	v_mfma_f32_16x16x32_bf16 v[90:93], v[138:141], v[190:193], v[90:93]
	v_mfma_f32_16x16x32_bf16 v[78:81], v[130:133], v[202:205], v[78:81]
	v_mfma_f32_16x16x32_bf16 v[74:77], v[138:141], v[202:205], v[74:77]
	v_mfma_f32_16x16x32_bf16 v[126:129], v[134:137], v[178:181], v[126:129]
	v_mfma_f32_16x16x32_bf16 v[122:125], v[142:145], v[178:181], v[122:125]
	v_mfma_f32_16x16x32_bf16 v[110:113], v[134:137], v[186:189], v[110:113]
	v_mfma_f32_16x16x32_bf16 v[106:109], v[142:145], v[186:189], v[106:109]
	v_mfma_f32_16x16x32_bf16 v[94:97], v[134:137], v[194:197], v[94:97]
	v_mfma_f32_16x16x32_bf16 v[90:93], v[142:145], v[194:197], v[90:93]
	v_mfma_f32_16x16x32_bf16 v[78:81], v[134:137], v[206:209], v[78:81]
	v_mfma_f32_16x16x32_bf16 v[74:77], v[142:145], v[206:209], v[74:77]
	s_setprio 0
	s_barrier
	s_add_i32 s46, 0, 0x1c000
	s_add_i32 s47, s76, s65
	v_add_u32_e32 v201, s46, v177
	v_lshl_add_u64 v[198:199], v[198:199], 0, s[16:17]
	s_mov_b32 m0, s47
	ds_read_b128 v[210:213], v201
	ds_read_b128 v[214:217], v201 offset:1024
	ds_read_b128 v[218:221], v201 offset:2048
	ds_read_b128 v[222:225], v201 offset:3072
	global_load_lds_dwordx4 v[198:199], off
	v_lshl_add_u64 v[198:199], v[226:227], 0, s[16:17]
	s_add_i32 m0, s47, 0x2000
	s_nop 0
	global_load_lds_dwordx4 v[198:199], off
	s_barrier
	s_waitcnt lgkmcnt(0)
	s_setprio 1
	v_mfma_f32_16x16x32_bf16 v[118:121], v[210:213], v[166:169], v[118:121]
	v_mfma_f32_16x16x32_bf16 v[114:117], v[218:221], v[166:169], v[114:117]
	v_mfma_f32_16x16x32_bf16 v[102:105], v[210:213], v[182:185], v[102:105]
	v_mfma_f32_16x16x32_bf16 v[98:101], v[218:221], v[182:185], v[98:101]
	v_mfma_f32_16x16x32_bf16 v[86:89], v[210:213], v[190:193], v[86:89]
	v_mfma_f32_16x16x32_bf16 v[82:85], v[218:221], v[190:193], v[82:85]
	v_mfma_f32_16x16x32_bf16 v[70:73], v[210:213], v[202:205], v[70:73]
	v_mfma_f32_16x16x32_bf16 v[66:69], v[218:221], v[202:205], v[66:69]
	v_mfma_f32_16x16x32_bf16 v[118:121], v[214:217], v[178:181], v[118:121]
	v_mfma_f32_16x16x32_bf16 v[114:117], v[222:225], v[178:181], v[114:117]
	v_mfma_f32_16x16x32_bf16 v[102:105], v[214:217], v[186:189], v[102:105]
	v_mfma_f32_16x16x32_bf16 v[98:101], v[222:225], v[186:189], v[98:101]
	v_mfma_f32_16x16x32_bf16 v[86:89], v[214:217], v[194:197], v[86:89]
	v_mfma_f32_16x16x32_bf16 v[82:85], v[222:225], v[194:197], v[82:85]
	v_mfma_f32_16x16x32_bf16 v[70:73], v[214:217], v[206:209], v[70:73]
	v_mfma_f32_16x16x32_bf16 v[66:69], v[222:225], v[206:209], v[66:69]
	s_setprio 0
	s_barrier
	s_mov_b32 m0, s70
	v_lshl_add_u64 v[198:199], v[228:229], 0, s[16:17]
	ds_read_b128 v[166:169], v156 offset:49152
	ds_read_b128 v[178:181], v156 offset:50176
	ds_read_b128 v[182:185], v156 offset:51200
	ds_read_b128 v[186:189], v156 offset:52224
	ds_read_b128 v[190:193], v156 offset:53248
	ds_read_b128 v[194:197], v156 offset:54272
	ds_read_b128 v[202:205], v156 offset:55296
	ds_read_b128 v[206:209], v156 offset:56320
	global_load_lds_dwordx4 v[198:199], off
	v_lshl_add_u64 v[198:199], v[230:231], 0, s[16:17]
	s_mov_b32 m0, s71
	s_nop 0
	global_load_lds_dwordx4 v[198:199], off
	s_barrier
	s_waitcnt lgkmcnt(0)
	s_setprio 1
	v_mfma_f32_16x16x32_bf16 v[62:65], v[130:133], v[166:169], v[62:65]
	v_mfma_f32_16x16x32_bf16 v[58:61], v[138:141], v[166:169], v[58:61]
	v_mfma_f32_16x16x32_bf16 v[46:49], v[130:133], v[182:185], v[46:49]
	v_mfma_f32_16x16x32_bf16 v[42:45], v[138:141], v[182:185], v[42:45]
	v_mfma_f32_16x16x32_bf16 v[30:33], v[130:133], v[190:193], v[30:33]
	v_mfma_f32_16x16x32_bf16 v[26:29], v[138:141], v[190:193], v[26:29]
	v_mfma_f32_16x16x32_bf16 v[14:17], v[130:133], v[202:205], v[14:17]
	v_mfma_f32_16x16x32_bf16 v[10:13], v[138:141], v[202:205], v[10:13]
	v_mfma_f32_16x16x32_bf16 v[62:65], v[134:137], v[178:181], v[62:65]
	v_mfma_f32_16x16x32_bf16 v[58:61], v[142:145], v[178:181], v[58:61]
	v_mfma_f32_16x16x32_bf16 v[46:49], v[134:137], v[186:189], v[46:49]
	v_mfma_f32_16x16x32_bf16 v[42:45], v[142:145], v[186:189], v[42:45]
	v_mfma_f32_16x16x32_bf16 v[30:33], v[134:137], v[194:197], v[30:33]
	v_mfma_f32_16x16x32_bf16 v[26:29], v[142:145], v[194:197], v[26:29]
	v_mfma_f32_16x16x32_bf16 v[14:17], v[134:137], v[206:209], v[14:17]
	v_mfma_f32_16x16x32_bf16 v[10:13], v[142:145], v[206:209], v[10:13]
	s_setprio 0
	s_barrier
	s_add_u32 s44, s44, 0x20080
	s_addc_u32 s45, s45, 0
	s_add_i32 s46, s46, s65
	v_lshl_add_u64 v[130:131], s[44:45], 0, v[150:151]
	s_mov_b32 m0, s46
	s_nop 0
	global_load_lds_dwordx4 v[130:131], off
	v_lshl_add_u64 v[130:131], s[44:45], 0, v[154:155]
	s_add_i32 m0, s46, 0x2000
	s_nop 0
	global_load_lds_dwordx4 v[130:131], off
	s_waitcnt vmcnt(6)
	s_barrier
	s_setprio 1
	v_mfma_f32_16x16x32_bf16 v[54:57], v[210:213], v[166:169], v[54:57]
	v_mfma_f32_16x16x32_bf16 v[50:53], v[218:221], v[166:169], v[50:53]
	v_mfma_f32_16x16x32_bf16 v[38:41], v[210:213], v[182:185], v[38:41]
	v_mfma_f32_16x16x32_bf16 v[34:37], v[218:221], v[182:185], v[34:37]
	v_mfma_f32_16x16x32_bf16 v[22:25], v[210:213], v[190:193], v[22:25]
	v_mfma_f32_16x16x32_bf16 v[18:21], v[218:221], v[190:193], v[18:21]
	v_mfma_f32_16x16x32_bf16 v[6:9], v[210:213], v[202:205], v[6:9]
	v_mfma_f32_16x16x32_bf16 v[2:5], v[218:221], v[202:205], v[2:5]
	v_mfma_f32_16x16x32_bf16 v[54:57], v[214:217], v[178:181], v[54:57]
	v_mfma_f32_16x16x32_bf16 v[50:53], v[222:225], v[178:181], v[50:53]
	v_mfma_f32_16x16x32_bf16 v[38:41], v[214:217], v[186:189], v[38:41]
	v_mfma_f32_16x16x32_bf16 v[34:37], v[222:225], v[186:189], v[34:37]
	v_mfma_f32_16x16x32_bf16 v[22:25], v[214:217], v[194:197], v[22:25]
	v_mfma_f32_16x16x32_bf16 v[18:21], v[222:225], v[194:197], v[18:21]
	v_mfma_f32_16x16x32_bf16 v[6:9], v[214:217], v[206:209], v[6:9]
	v_mfma_f32_16x16x32_bf16 v[2:5], v[222:225], v[206:209], v[2:5]
	s_setprio 0
	s_barrier
	s_add_i32 s75, s75, 2
	s_add_u32 s42, s42, 0x100
	s_addc_u32 s43, s43, 0
	s_add_u32 s73, s73, 0x100
	s_addc_u32 s74, s74, 0
	s_cmp_gt_u32 s75, 5
	s_cbranch_scc0 .LBB0_710
	global_load_dwordx4 v[138:141], v[162:163], off offset:16
	global_load_dwordx4 v[142:145], v[162:163], off
	global_load_dwordx4 v[130:133], v[162:163], off offset:528
	global_load_dwordx4 v[134:137], v[162:163], off offset:512
	s_cmp_lt_i32 s40, 48
	s_cselect_b32 s25, s50, 0xffffd000
	s_cselect_b32 s41, 0x4000, s49
	s_cmp_lt_i32 s40, 32
	s_cselect_b64 vcc, -1, 0
	s_and_b64 s[42:43], vcc, exec
	s_cselect_b32 s42, 0, s25
	v_lshl_add_u32 v167, s40, 8, v176
	v_add_u32_e32 v178, s42, v167
	v_cndmask_b32_e32 v166, v174, v175, vcc
	v_cmp_ne_u32_e32 vcc, 0, v178
	s_cselect_b32 s27, s48, 0x2000
	s_cselect_b32 s25, 0, s41
	v_mov_b32_e32 v168, v166
	v_mov_b32_e32 v169, v166
	s_or_b64 s[46:47], s[20:21], vcc
	s_mov_b64 s[40:41], 0
	s_mov_b64 s[44:45], 0
	s_and_saveexec_b64 s[42:43], s[46:47]
	s_cbranch_execz .LBB0_713
	v_sub_u32_e32 v167, s27, v178
	v_cndmask_b32_e64 v167, v178, v167, s[4:5]
	v_add_u32_e32 v180, s25, v167
	v_ashrrev_i32_e32 v181, 31, v180
	v_lshlrev_b64 v[180:181], 11, v[180:181]
	v_mov_b32_e32 v167, v166
	v_lshl_add_u64 v[180:181], v[164:165], 0, v[180:181]
	s_waitcnt vmcnt(0)
	v_pk_fma_f32 v[128:129], v[166:167], v[128:129], v[144:145]
	v_pk_fma_f32 v[126:127], v[168:169], v[126:127], v[142:143]
	v_pk_fma_f32 v[182:183], v[166:167], v[124:125], v[140:141]
	v_pk_fma_f32 v[124:125], v[168:169], v[122:123], v[138:139]
	v_cvt_pk_bf16_f32 v122, v126, v127
	v_cvt_pk_bf16_f32 v123, v128, v129
	s_and_b64 s[44:45], s[0:1], exec
	v_cvt_pk_bf16_f32 v124, v124, v125
	v_cvt_pk_bf16_f32 v125, v182, v183
	global_store_dwordx4 v[180:181], v[122:125], off
	v_pk_fma_f32 v[120:121], v[166:167], v[120:121], v[136:137]
	v_pk_fma_f32 v[118:119], v[168:169], v[118:119], v[134:135]
	v_pk_fma_f32 v[122:123], v[166:167], v[116:117], v[132:133]
	v_pk_fma_f32 v[116:117], v[168:169], v[114:115], v[130:131]
	v_cvt_pk_bf16_f32 v114, v118, v119
	v_cvt_pk_bf16_f32 v115, v120, v121
	s_nop 0
	v_cvt_pk_bf16_f32 v116, v116, v117
	v_cvt_pk_bf16_f32 v117, v122, v123
	global_store_dwordx4 v[180:181], v[114:117], off offset:256

.LBB0_909:
	ds_read_b128 v[154:157], v151
	ds_read_b128 v[158:161], v151 offset:1024
	ds_read_b128 v[162:165], v151 offset:2048
	ds_read_b128 v[166:169], v151 offset:3072
	s_add_u32 s42, s40, 0xfff80080
	s_addc_u32 s43, s41, -1
	s_cmp_eq_u32 s70, 28
	s_cselect_b32 s45, s25, s43
	s_cselect_b32 s44, s66, s42
	s_cselect_b32 s43, s23, s69
	s_cselect_b32 s42, s67, s68
	v_lshl_add_u64 v[148:149], s[40:41], 0, v[138:139]
	s_add_i32 m0, s34, 0xc000
	ds_read_b128 v[170:173], v152
	ds_read_b128 v[174:177], v152 offset:1024
	ds_read_b128 v[178:181], v152 offset:2048
	ds_read_b128 v[182:185], v152 offset:3072
	ds_read_b128 v[186:189], v152 offset:4096
	ds_read_b128 v[190:193], v152 offset:5120
	ds_read_b128 v[194:197], v152 offset:6144
	ds_read_b128 v[198:201], v152 offset:7168
	global_load_lds_dwordx4 v[148:149], off
	v_lshl_add_u64 v[148:149], s[40:41], 0, v[140:141]
	s_add_i32 m0, s34, 0xe000
	s_nop 0
	global_load_lds_dwordx4 v[148:149], off
	s_waitcnt lgkmcnt(8)
	s_barrier
	s_waitcnt lgkmcnt(0)
	s_setprio 1
	v_mfma_f32_16x16x32_bf16 v[126:129], v[154:157], v[170:173], v[126:129]
	v_mfma_f32_16x16x32_bf16 v[122:125], v[162:165], v[170:173], v[122:125]
	v_mfma_f32_16x16x32_bf16 v[114:117], v[154:157], v[178:181], v[114:117]
	v_mfma_f32_16x16x32_bf16 v[106:109], v[162:165], v[178:181], v[106:109]
	v_mfma_f32_16x16x32_bf16 v[98:101], v[154:157], v[186:189], v[98:101]
	v_mfma_f32_16x16x32_bf16 v[90:93], v[162:165], v[186:189], v[90:93]
	v_mfma_f32_16x16x32_bf16 v[82:85], v[154:157], v[194:197], v[82:85]
	v_mfma_f32_16x16x32_bf16 v[74:77], v[162:165], v[194:197], v[74:77]
	v_mfma_f32_16x16x32_bf16 v[126:129], v[158:161], v[174:177], v[126:129]
	v_mfma_f32_16x16x32_bf16 v[122:125], v[166:169], v[174:177], v[122:125]
	v_mfma_f32_16x16x32_bf16 v[114:117], v[158:161], v[182:185], v[114:117]
	v_mfma_f32_16x16x32_bf16 v[106:109], v[166:169], v[182:185], v[106:109]
	v_mfma_f32_16x16x32_bf16 v[98:101], v[158:161], v[190:193], v[98:101]
	v_mfma_f32_16x16x32_bf16 v[90:93], v[166:169], v[190:193], v[90:93]
	v_mfma_f32_16x16x32_bf16 v[82:85], v[158:161], v[198:201], v[82:85]
	v_mfma_f32_16x16x32_bf16 v[74:77], v[166:169], v[198:201], v[74:77]
	s_setprio 0
	s_barrier
	s_add_i32 s71, s51, s33
	v_lshl_add_u64 v[148:149], s[42:43], 0, v[132:133]
	s_mov_b32 m0, s71
	ds_read_b128 v[202:205], v153
	ds_read_b128 v[206:209], v153 offset:1024
	ds_read_b128 v[210:213], v153 offset:2048
	ds_read_b128 v[214:217], v153 offset:3072
	global_load_lds_dwordx4 v[148:149], off
	v_lshl_add_u64 v[218:219], s[42:43], 0, v[136:137]
	s_add_i32 m0, s71, 0x2000
	s_nop 0
	global_load_lds_dwordx4 v[218:219], off
	s_barrier
	s_waitcnt lgkmcnt(0)
	s_setprio 1
	v_mfma_f32_16x16x32_bf16 v[118:121], v[202:205], v[170:173], v[118:121]
	v_mfma_f32_16x16x32_bf16 v[110:113], v[210:213], v[170:173], v[110:113]
	v_mfma_f32_16x16x32_bf16 v[102:105], v[202:205], v[178:181], v[102:105]
	v_mfma_f32_16x16x32_bf16 v[94:97], v[210:213], v[178:181], v[94:97]
	v_mfma_f32_16x16x32_bf16 v[86:89], v[202:205], v[186:189], v[86:89]
	v_mfma_f32_16x16x32_bf16 v[78:81], v[210:213], v[186:189], v[78:81]
	v_mfma_f32_16x16x32_bf16 v[70:73], v[202:205], v[194:197], v[70:73]
	v_mfma_f32_16x16x32_bf16 v[66:69], v[210:213], v[194:197], v[66:69]
	v_mfma_f32_16x16x32_bf16 v[118:121], v[206:209], v[174:177], v[118:121]
	v_mfma_f32_16x16x32_bf16 v[110:113], v[214:217], v[174:177], v[110:113]
	v_mfma_f32_16x16x32_bf16 v[102:105], v[206:209], v[182:185], v[102:105]
	v_mfma_f32_16x16x32_bf16 v[94:97], v[214:217], v[182:185], v[94:97]
	v_mfma_f32_16x16x32_bf16 v[86:89], v[206:209], v[190:193], v[86:89]
	v_mfma_f32_16x16x32_bf16 v[78:81], v[214:217], v[190:193], v[78:81]
	v_mfma_f32_16x16x32_bf16 v[70:73], v[206:209], v[198:201], v[70:73]
	v_mfma_f32_16x16x32_bf16 v[66:69], v[214:217], v[198:201], v[66:69]
	s_setprio 0
	s_barrier
	s_mov_b32 m0, s34
	v_lshl_add_u64 v[220:221], s[44:45], 0, v[130:131]
	ds_read_b128 v[170:173], v152 offset:16384
	ds_read_b128 v[174:177], v152 offset:17408
	ds_read_b128 v[178:181], v152 offset:18432
	ds_read_b128 v[182:185], v152 offset:19456
	ds_read_b128 v[186:189], v152 offset:20480
	ds_read_b128 v[190:193], v152 offset:21504
	ds_read_b128 v[194:197], v152 offset:22528
	ds_read_b128 v[198:201], v152 offset:23552
	global_load_lds_dwordx4 v[220:221], off
	v_lshl_add_u64 v[222:223], s[44:45], 0, v[134:135]
	s_mov_b32 m0, s35
	s_nop 0
	global_load_lds_dwordx4 v[222:223], off
	s_barrier
	s_waitcnt lgkmcnt(0)
	s_setprio 1
	v_mfma_f32_16x16x32_bf16 v[62:65], v[154:157], v[170:173], v[62:65]
	v_mfma_f32_16x16x32_bf16 v[58:61], v[162:165], v[170:173], v[58:61]
	v_mfma_f32_16x16x32_bf16 v[54:57], v[154:157], v[178:181], v[54:57]
	v_mfma_f32_16x16x32_bf16 v[46:49], v[162:165], v[178:181], v[46:49]
	v_mfma_f32_16x16x32_bf16 v[38:41], v[154:157], v[186:189], v[38:41]
	v_mfma_f32_16x16x32_bf16 v[30:33], v[162:165], v[186:189], v[30:33]
	v_mfma_f32_16x16x32_bf16 v[22:25], v[154:157], v[194:197], v[22:25]
	v_mfma_f32_16x16x32_bf16 v[14:17], v[162:165], v[194:197], v[14:17]
	v_mfma_f32_16x16x32_bf16 v[62:65], v[158:161], v[174:177], v[62:65]
	v_mfma_f32_16x16x32_bf16 v[58:61], v[166:169], v[174:177], v[58:61]
	v_mfma_f32_16x16x32_bf16 v[54:57], v[158:161], v[182:185], v[54:57]
	v_mfma_f32_16x16x32_bf16 v[46:49], v[166:169], v[182:185], v[46:49]
	v_mfma_f32_16x16x32_bf16 v[38:41], v[158:161], v[190:193], v[38:41]
	v_mfma_f32_16x16x32_bf16 v[30:33], v[166:169], v[190:193], v[30:33]
	v_mfma_f32_16x16x32_bf16 v[22:25], v[158:161], v[198:201], v[22:25]
	v_mfma_f32_16x16x32_bf16 v[14:17], v[166:169], v[198:201], v[14:17]
	s_setprio 0
	s_barrier
	s_add_u32 s72, s42, 0x80000
	s_addc_u32 s73, s43, 0
	s_add_i32 s71, s60, s33
	v_lshl_add_u64 v[154:155], s[72:73], 0, v[132:133]
	s_mov_b32 m0, s71
	s_nop 0
	global_load_lds_dwordx4 v[154:155], off
	v_lshl_add_u64 v[154:155], s[72:73], 0, v[136:137]
	s_add_i32 m0, s71, 0x2000
	s_nop 0
	global_load_lds_dwordx4 v[154:155], off
	s_waitcnt vmcnt(6)
	s_barrier
	s_setprio 1
	v_mfma_f32_16x16x32_bf16 v[50:53], v[202:205], v[170:173], v[50:53]
	v_mfma_f32_16x16x32_bf16 v[42:45], v[210:213], v[170:173], v[42:45]
	v_mfma_f32_16x16x32_bf16 v[34:37], v[202:205], v[178:181], v[34:37]
	v_mfma_f32_16x16x32_bf16 v[26:29], v[210:213], v[178:181], v[26:29]
	v_mfma_f32_16x16x32_bf16 v[18:21], v[202:205], v[186:189], v[18:21]
	v_mfma_f32_16x16x32_bf16 v[10:13], v[210:213], v[186:189], v[10:13]
	v_mfma_f32_16x16x32_bf16 v[6:9], v[202:205], v[194:197], v[6:9]
	v_mfma_f32_16x16x32_bf16 v[2:5], v[210:213], v[194:197], v[2:5]
	v_mfma_f32_16x16x32_bf16 v[50:53], v[206:209], v[174:177], v[50:53]
	v_mfma_f32_16x16x32_bf16 v[42:45], v[214:217], v[174:177], v[42:45]
	v_mfma_f32_16x16x32_bf16 v[34:37], v[206:209], v[182:185], v[34:37]
	v_mfma_f32_16x16x32_bf16 v[26:29], v[214:217], v[182:185], v[26:29]
	v_mfma_f32_16x16x32_bf16 v[18:21], v[206:209], v[190:193], v[18:21]
	v_mfma_f32_16x16x32_bf16 v[10:13], v[214:217], v[190:193], v[10:13]
	v_mfma_f32_16x16x32_bf16 v[6:9], v[206:209], v[198:201], v[6:9]
	v_mfma_f32_16x16x32_bf16 v[2:5], v[214:217], v[198:201], v[2:5]
	s_setprio 0
	s_barrier
	s_add_i32 s71, 0, 0x18000
	v_add_u32_e32 v166, s71, v147
	ds_read_b128 v[154:157], v166
	ds_read_b128 v[158:161], v166 offset:1024
	ds_read_b128 v[162:165], v166 offset:2048
	ds_read_b128 v[166:169], v166 offset:3072
	s_add_u32 s44, s44, 0x80000
	s_addc_u32 s45, s45, 0
	s_mov_b32 m0, s39
	v_lshl_add_u64 v[202:203], s[44:45], 0, v[130:131]
	ds_read_b128 v[170:173], v152 offset:32768
	ds_read_b128 v[174:177], v152 offset:33792
	ds_read_b128 v[178:181], v152 offset:34816
	ds_read_b128 v[182:185], v152 offset:35840
	ds_read_b128 v[186:189], v152 offset:36864
	ds_read_b128 v[190:193], v152 offset:37888
	ds_read_b128 v[194:197], v152 offset:38912
	ds_read_b128 v[198:201], v152 offset:39936
	global_load_lds_dwordx4 v[202:203], off
	v_lshl_add_u64 v[202:203], s[44:45], 0, v[134:135]
	s_mov_b32 m0, s46
	s_nop 0
	global_load_lds_dwordx4 v[202:203], off
	s_waitcnt lgkmcnt(8)
	s_barrier
	s_waitcnt lgkmcnt(0)
	s_setprio 1
	v_mfma_f32_16x16x32_bf16 v[126:129], v[154:157], v[170:173], v[126:129]
	v_mfma_f32_16x16x32_bf16 v[122:125], v[162:165], v[170:173], v[122:125]
	v_mfma_f32_16x16x32_bf16 v[114:117], v[154:157], v[178:181], v[114:117]
	v_mfma_f32_16x16x32_bf16 v[106:109], v[162:165], v[178:181], v[106:109]
	v_mfma_f32_16x16x32_bf16 v[98:101], v[154:157], v[186:189], v[98:101]
	v_mfma_f32_16x16x32_bf16 v[90:93], v[162:165], v[186:189], v[90:93]
	v_mfma_f32_16x16x32_bf16 v[82:85], v[154:157], v[194:197], v[82:85]
	v_mfma_f32_16x16x32_bf16 v[74:77], v[162:165], v[194:197], v[74:77]
	v_mfma_f32_16x16x32_bf16 v[126:129], v[158:161], v[174:177], v[126:129]
	v_mfma_f32_16x16x32_bf16 v[122:125], v[166:169], v[174:177], v[122:125]
	v_mfma_f32_16x16x32_bf16 v[114:117], v[158:161], v[182:185], v[114:117]
	v_mfma_f32_16x16x32_bf16 v[106:109], v[166:169], v[182:185], v[106:109]
	v_mfma_f32_16x16x32_bf16 v[98:101], v[158:161], v[190:193], v[98:101]
	v_mfma_f32_16x16x32_bf16 v[90:93], v[166:169], v[190:193], v[90:93]
	v_mfma_f32_16x16x32_bf16 v[82:85], v[158:161], v[198:201], v[82:85]
	v_mfma_f32_16x16x32_bf16 v[74:77], v[166:169], v[198:201], v[74:77]
	s_setprio 0
	s_barrier
	s_add_i32 s44, 0, 0x1c000
	s_add_i32 s45, s71, s33
	v_add_u32_e32 v214, s44, v147
	v_lshl_add_u64 v[148:149], v[148:149], 0, s[10:11]
	s_mov_b32 m0, s45
	ds_read_b128 v[202:205], v214
	ds_read_b128 v[206:209], v214 offset:1024
	ds_read_b128 v[210:213], v214 offset:2048
	ds_read_b128 v[214:217], v214 offset:3072
	global_load_lds_dwordx4 v[148:149], off
	v_lshl_add_u64 v[148:149], v[218:219], 0, s[10:11]
	s_add_i32 m0, s45, 0x2000
	s_nop 0
	global_load_lds_dwordx4 v[148:149], off
	s_barrier
	s_waitcnt lgkmcnt(0)
	s_setprio 1
	v_mfma_f32_16x16x32_bf16 v[118:121], v[202:205], v[170:173], v[118:121]
	v_mfma_f32_16x16x32_bf16 v[110:113], v[210:213], v[170:173], v[110:113]
	v_mfma_f32_16x16x32_bf16 v[102:105], v[202:205], v[178:181], v[102:105]
	v_mfma_f32_16x16x32_bf16 v[94:97], v[210:213], v[178:181], v[94:97]
	v_mfma_f32_16x16x32_bf16 v[86:89], v[202:205], v[186:189], v[86:89]
	v_mfma_f32_16x16x32_bf16 v[78:81], v[210:213], v[186:189], v[78:81]
	v_mfma_f32_16x16x32_bf16 v[70:73], v[202:205], v[194:197], v[70:73]
	v_mfma_f32_16x16x32_bf16 v[66:69], v[210:213], v[194:197], v[66:69]
	v_mfma_f32_16x16x32_bf16 v[118:121], v[206:209], v[174:177], v[118:121]
	v_mfma_f32_16x16x32_bf16 v[110:113], v[214:217], v[174:177], v[110:113]
	v_mfma_f32_16x16x32_bf16 v[102:105], v[206:209], v[182:185], v[102:105]
	v_mfma_f32_16x16x32_bf16 v[94:97], v[214:217], v[182:185], v[94:97]
	v_mfma_f32_16x16x32_bf16 v[86:89], v[206:209], v[190:193], v[86:89]
	v_mfma_f32_16x16x32_bf16 v[78:81], v[214:217], v[190:193], v[78:81]
	v_mfma_f32_16x16x32_bf16 v[70:73], v[206:209], v[198:201], v[70:73]
	v_mfma_f32_16x16x32_bf16 v[66:69], v[214:217], v[198:201], v[66:69]
	s_setprio 0
	s_barrier
	s_mov_b32 m0, s48
	v_lshl_add_u64 v[148:149], v[220:221], 0, s[10:11]
	ds_read_b128 v[170:173], v152 offset:49152
	ds_read_b128 v[174:177], v152 offset:50176
	ds_read_b128 v[178:181], v152 offset:51200
	ds_read_b128 v[182:185], v152 offset:52224
	ds_read_b128 v[186:189], v152 offset:53248
	ds_read_b128 v[190:193], v152 offset:54272
	ds_read_b128 v[194:197], v152 offset:55296
	ds_read_b128 v[198:201], v152 offset:56320
	global_load_lds_dwordx4 v[148:149], off
	v_lshl_add_u64 v[148:149], v[222:223], 0, s[10:11]
	s_mov_b32 m0, s49
	s_nop 0
	global_load_lds_dwordx4 v[148:149], off
	s_barrier
	s_waitcnt lgkmcnt(0)
	s_setprio 1
	v_mfma_f32_16x16x32_bf16 v[62:65], v[154:157], v[170:173], v[62:65]
	v_mfma_f32_16x16x32_bf16 v[58:61], v[162:165], v[170:173], v[58:61]
	v_mfma_f32_16x16x32_bf16 v[54:57], v[154:157], v[178:181], v[54:57]
	v_mfma_f32_16x16x32_bf16 v[46:49], v[162:165], v[178:181], v[46:49]
	v_mfma_f32_16x16x32_bf16 v[38:41], v[154:157], v[186:189], v[38:41]
	v_mfma_f32_16x16x32_bf16 v[30:33], v[162:165], v[186:189], v[30:33]
	v_mfma_f32_16x16x32_bf16 v[22:25], v[154:157], v[194:197], v[22:25]
	v_mfma_f32_16x16x32_bf16 v[14:17], v[162:165], v[194:197], v[14:17]
	v_mfma_f32_16x16x32_bf16 v[62:65], v[158:161], v[174:177], v[62:65]
	v_mfma_f32_16x16x32_bf16 v[58:61], v[166:169], v[174:177], v[58:61]
	v_mfma_f32_16x16x32_bf16 v[54:57], v[158:161], v[182:185], v[54:57]
	v_mfma_f32_16x16x32_bf16 v[46:49], v[166:169], v[182:185], v[46:49]
	v_mfma_f32_16x16x32_bf16 v[38:41], v[158:161], v[190:193], v[38:41]
	v_mfma_f32_16x16x32_bf16 v[30:33], v[166:169], v[190:193], v[30:33]
	v_mfma_f32_16x16x32_bf16 v[22:25], v[158:161], v[198:201], v[22:25]
	v_mfma_f32_16x16x32_bf16 v[14:17], v[166:169], v[198:201], v[14:17]
	s_setprio 0
	s_barrier
	s_add_u32 s42, s42, 0x80080
	s_addc_u32 s43, s43, 0
	s_add_i32 s44, s44, s33
	v_lshl_add_u64 v[148:149], s[42:43], 0, v[132:133]
	s_mov_b32 m0, s44
	s_nop 0
	global_load_lds_dwordx4 v[148:149], off
	v_lshl_add_u64 v[148:149], s[42:43], 0, v[136:137]
	s_add_i32 m0, s44, 0x2000
	s_nop 0
	global_load_lds_dwordx4 v[148:149], off
	s_waitcnt vmcnt(6)
	s_barrier
	s_setprio 1
	v_mfma_f32_16x16x32_bf16 v[50:53], v[202:205], v[170:173], v[50:53]
	v_mfma_f32_16x16x32_bf16 v[42:45], v[210:213], v[170:173], v[42:45]
	v_mfma_f32_16x16x32_bf16 v[34:37], v[202:205], v[178:181], v[34:37]
	v_mfma_f32_16x16x32_bf16 v[26:29], v[210:213], v[178:181], v[26:29]
	v_mfma_f32_16x16x32_bf16 v[18:21], v[202:205], v[186:189], v[18:21]
	v_mfma_f32_16x16x32_bf16 v[10:13], v[210:213], v[186:189], v[10:13]
	v_mfma_f32_16x16x32_bf16 v[6:9], v[202:205], v[194:197], v[6:9]
	v_mfma_f32_16x16x32_bf16 v[2:5], v[210:213], v[194:197], v[2:5]
	v_mfma_f32_16x16x32_bf16 v[50:53], v[206:209], v[174:177], v[50:53]
	v_mfma_f32_16x16x32_bf16 v[42:45], v[214:217], v[174:177], v[42:45]
	v_mfma_f32_16x16x32_bf16 v[34:37], v[206:209], v[182:185], v[34:37]
	v_mfma_f32_16x16x32_bf16 v[26:29], v[214:217], v[182:185], v[26:29]
	v_mfma_f32_16x16x32_bf16 v[18:21], v[206:209], v[190:193], v[18:21]
	v_mfma_f32_16x16x32_bf16 v[10:13], v[214:217], v[190:193], v[10:13]
	v_mfma_f32_16x16x32_bf16 v[6:9], v[206:209], v[198:201], v[6:9]
	v_mfma_f32_16x16x32_bf16 v[2:5], v[214:217], v[198:201], v[2:5]
	s_setprio 0
	s_barrier
	s_add_i32 s70, s70, 2
	s_add_u32 s40, s40, 0x100
	s_addc_u32 s41, s41, 0
	s_add_u32 s68, s68, 0x100
	s_addc_u32 s69, s69, 0
	s_cmp_gt_u32 s70, 29
	s_cbranch_scc0 .LBB0_909
	v_lshl_add_u32 v154, s38, 8, v1
	v_lshl_or_b32 v148, s65, 8, v150
	v_ashrrev_i32_e32 v155, 31, v154
	v_ashrrev_i32_e32 v149, 31, v148
	v_lshlrev_b64 v[156:157], 12, v[154:155]
	v_lshl_add_u64 v[156:157], s[8:9], 0, v[156:157]
	v_lshlrev_b64 v[158:159], 1, v[148:149]
	v_lshl_add_u64 v[148:149], v[156:157], 0, v[158:159]
	v_cvt_pk_bf16_f32 v126, v126, v127
	v_cvt_pk_bf16_f32 v127, v128, v129
	v_cvt_pk_bf16_f32 v128, v122, v123
	v_cvt_pk_bf16_f32 v129, v124, v125
	global_store_dwordx4 v[148:149], v[126:129], off
	v_cvt_pk_bf16_f32 v118, v118, v119
	v_cvt_pk_bf16_f32 v119, v120, v121
	v_cvt_pk_bf16_f32 v120, v110, v111
	v_or_b32_e32 v110, 16, v154
	v_ashrrev_i32_e32 v111, 31, v110
	v_lshlrev_b64 v[110:111], 12, v[110:111]
	v_lshl_add_u64 v[110:111], s[8:9], 0, v[110:111]
	v_cvt_pk_bf16_f32 v121, v112, v113
	global_store_dwordx4 v[148:149], v[118:121], off offset:256
	s_mov_b32 s65, s22
	s_mov_b32 s38, s24
	v_lshl_add_u64 v[118:119], v[110:111], 0, v[158:159]
	v_cvt_pk_bf16_f32 v110, v114, v115
	v_cvt_pk_bf16_f32 v111, v116, v117
	v_cvt_pk_bf16_f32 v112, v106, v107
	v_cvt_pk_bf16_f32 v113, v108, v109
	global_store_dwordx4 v[118:119], v[110:113], off
	v_cvt_pk_bf16_f32 v102, v102, v103
	v_cvt_pk_bf16_f32 v103, v104, v105
	v_cvt_pk_bf16_f32 v104, v94, v95
	v_or_b32_e32 v94, 32, v154
	v_ashrrev_i32_e32 v95, 31, v94
	v_lshlrev_b64 v[94:95], 12, v[94:95]
	v_lshl_add_u64 v[94:95], s[8:9], 0, v[94:95]
	v_cvt_pk_bf16_f32 v105, v96, v97
	global_store_dwordx4 v[118:119], v[102:105], off offset:256
	s_mov_b64 s[42:43], s[36:37]
	s_mov_b64 s[40:41], s[26:27]
	v_lshl_add_u64 v[102:103], v[94:95], 0, v[158:159]
	v_cvt_pk_bf16_f32 v94, v98, v99
	v_cvt_pk_bf16_f32 v95, v100, v101
	v_cvt_pk_bf16_f32 v96, v90, v91
	v_cvt_pk_bf16_f32 v97, v92, v93
	global_store_dwordx4 v[102:103], v[94:97], off
	v_cvt_pk_bf16_f32 v86, v86, v87
	v_cvt_pk_bf16_f32 v87, v88, v89
	v_cvt_pk_bf16_f32 v88, v78, v79
	v_or_b32_e32 v78, 48, v154
	v_ashrrev_i32_e32 v79, 31, v78
	v_lshlrev_b64 v[78:79], 12, v[78:79]
	v_lshl_add_u64 v[78:79], s[8:9], 0, v[78:79]
	v_cvt_pk_bf16_f32 v89, v80, v81
	global_store_dwordx4 v[102:103], v[86:89], off offset:256
	s_nop 1
	v_lshl_add_u64 v[86:87], v[78:79], 0, v[158:159]
	v_cvt_pk_bf16_f32 v78, v82, v83
	v_cvt_pk_bf16_f32 v79, v84, v85
	v_cvt_pk_bf16_f32 v80, v74, v75
	v_cvt_pk_bf16_f32 v81, v76, v77
	global_store_dwordx4 v[86:87], v[78:81], off
	v_cvt_pk_bf16_f32 v70, v70, v71
	v_cvt_pk_bf16_f32 v71, v72, v73
	v_cvt_pk_bf16_f32 v72, v66, v67
	v_cvt_pk_bf16_f32 v73, v68, v69
	global_store_dwordx4 v[86:87], v[70:73], off offset:256
	v_cvt_pk_bf16_f32 v62, v62, v63
	v_cvt_pk_bf16_f32 v63, v64, v65
	v_cvt_pk_bf16_f32 v64, v58, v59
	v_add_co_u32_e32 v58, vcc, s61, v148
	v_lshl_add_u64 v[66:67], v[148:149], 0, s[6:7]
	s_nop 0
	v_addc_co_u32_e32 v59, vcc, 0, v149, vcc
	v_cvt_pk_bf16_f32 v65, v60, v61
	global_store_dwordx4 v[58:59], v[62:65], off
	v_cvt_pk_bf16_f32 v50, v50, v51
	v_cvt_pk_bf16_f32 v51, v52, v53
	v_cvt_pk_bf16_f32 v52, v42, v43
	v_cvt_pk_bf16_f32 v53, v44, v45
	global_store_dwordx4 v[66:67], v[50:53], off offset:256
	v_cvt_pk_bf16_f32 v42, v54, v55
	v_cvt_pk_bf16_f32 v43, v56, v57
	v_cvt_pk_bf16_f32 v44, v46, v47
	v_add_co_u32_e32 v46, vcc, s62, v148
	s_nop 0
	v_lshl_add_u64 v[50:51], v[148:149], 0, s[16:17]
	v_addc_co_u32_e32 v47, vcc, 0, v149, vcc
	v_cvt_pk_bf16_f32 v45, v48, v49
	global_store_dwordx4 v[46:47], v[42:45], off
	v_cvt_pk_bf16_f32 v34, v34, v35
	v_cvt_pk_bf16_f32 v35, v36, v37
	v_cvt_pk_bf16_f32 v36, v26, v27
	v_cvt_pk_bf16_f32 v37, v28, v29
	global_store_dwordx4 v[50:51], v[34:37], off offset:256
	v_cvt_pk_bf16_f32 v26, v38, v39
	v_cvt_pk_bf16_f32 v27, v40, v41
	v_cvt_pk_bf16_f32 v28, v30, v31
	v_add_co_u32_e32 v30, vcc, s63, v148
	s_nop 0
	v_lshl_add_u64 v[34:35], v[148:149], 0, s[18:19]
	v_addc_co_u32_e32 v31, vcc, 0, v149, vcc
	v_cvt_pk_bf16_f32 v29, v32, v33
	global_store_dwordx4 v[30:31], v[26:29], off
	v_cvt_pk_bf16_f32 v18, v18, v19
	v_cvt_pk_bf16_f32 v19, v20, v21
	v_cvt_pk_bf16_f32 v20, v10, v11
	v_cvt_pk_bf16_f32 v21, v12, v13
	global_store_dwordx4 v[34:35], v[18:21], off offset:256
	v_cvt_pk_bf16_f32 v10, v22, v23
	v_cvt_pk_bf16_f32 v11, v24, v25
	v_cvt_pk_bf16_f32 v12, v14, v15
	v_add_co_u32_e32 v14, vcc, s64, v148
	s_nop 0
	v_lshl_add_u64 v[18:19], v[148:149], 0, s[20:21]
	v_addc_co_u32_e32 v15, vcc, 0, v149, vcc
	s_and_b64 vcc, exec, s[0:1]
	v_cvt_pk_bf16_f32 v13, v16, v17
	global_store_dwordx4 v[14:15], v[10:13], off
	v_cvt_pk_bf16_f32 v6, v6, v7
	v_cvt_pk_bf16_f32 v7, v8, v9
	v_cvt_pk_bf16_f32 v8, v2, v3
	v_cvt_pk_bf16_f32 v9, v4, v5
	global_store_dwordx4 v[18:19], v[6:9], off offset:256
	s_cbranch_vccz .LBB0_902
	s_waitcnt vmcnt(0)
	s_cmpk_gt_u32 s3, 0xff
	s_cbranch_scc1 .LBB0_913
	s_barrier
